# GEMM K-loops: per-segment s_setprio toggles removed (64 scalar instructions per 4 loops)
# speedup vs baseline: 1.0187x; 1.0187x over previous
.LBB0_70:
	s_add_i32 s35, s18, 2
	s_add_u32 s16, s12, 0x100
	s_addc_u32 s17, s13, 0
	s_cmp_lg_u32 s34, s18
	s_cselect_b32 s22, s16, 0
	s_cselect_b32 s23, s17, 0
	s_add_u32 s18, s10, s22
	s_addc_u32 s19, s11, s23
	s_add_i32 s36, 0, 0x10000
	s_add_u32 s22, s8, s22
	s_addc_u32 s23, s9, s23
	v_lshl_add_u64 v[190:191], v[130:131], 0, s[12:13]
	s_add_i32 m0, s3, 0xc000
	ds_read_b128 v[170:173], v153
	ds_read_b128 v[178:181], v153 offset:2048
	ds_read_b128 v[186:189], v153 offset:4096
	ds_read_b128 v[220:223], v153 offset:6144
	ds_read_b128 v[174:177], v153 offset:1024
	ds_read_b128 v[182:185], v153 offset:3072
	ds_read_b128 v[216:219], v153 offset:5120
	ds_read_b128 v[224:227], v153 offset:7168
	global_load_lds_dwordx4 v[190:191], off
	v_lshl_add_u64 v[190:191], v[150:151], 0, s[12:13]
	s_add_i32 m0, s3, 0xe000
	s_nop 0
	global_load_lds_dwordx4 v[190:191], off
	s_waitcnt lgkmcnt(8)
	s_waitcnt vmcnt(10)
	s_barrier
	s_waitcnt lgkmcnt(4)
	v_mfma_f32_16x16x32_bf16 v[124:127], v[154:157], v[170:173], v[124:127]
	v_mfma_f32_16x16x32_bf16 v[120:123], v[162:165], v[170:173], v[120:123]
	v_mfma_f32_16x16x32_bf16 v[116:119], v[154:157], v[178:181], v[116:119]
	v_mfma_f32_16x16x32_bf16 v[108:111], v[162:165], v[178:181], v[108:111]
	v_mfma_f32_16x16x32_bf16 v[100:103], v[154:157], v[186:189], v[100:103]
	v_mfma_f32_16x16x32_bf16 v[92:95], v[162:165], v[186:189], v[92:95]
	v_mfma_f32_16x16x32_bf16 v[84:87], v[154:157], v[220:223], v[84:87]
	v_mfma_f32_16x16x32_bf16 v[76:79], v[162:165], v[220:223], v[76:79]
	s_waitcnt lgkmcnt(0)
	v_mfma_f32_16x16x32_bf16 v[124:127], v[158:161], v[174:177], v[124:127]
	v_mfma_f32_16x16x32_bf16 v[120:123], v[166:169], v[174:177], v[120:123]
	v_mfma_f32_16x16x32_bf16 v[116:119], v[158:161], v[182:185], v[116:119]
	v_mfma_f32_16x16x32_bf16 v[108:111], v[166:169], v[182:185], v[108:111]
	v_mfma_f32_16x16x32_bf16 v[100:103], v[158:161], v[216:219], v[100:103]
	v_mfma_f32_16x16x32_bf16 v[92:95], v[166:169], v[216:219], v[92:95]
	v_mfma_f32_16x16x32_bf16 v[84:87], v[158:161], v[224:227], v[84:87]
	v_mfma_f32_16x16x32_bf16 v[76:79], v[166:169], v[224:227], v[76:79]
	s_barrier
	s_add_i32 s37, 0, 0x14000
	v_add_u32_e32 v190, s37, v152
	s_add_i32 s12, s36, s26
	ds_read_b128 v[228:231], v190
	ds_read_b128 v[236:239], v190 offset:2048
	ds_read_b128 v[232:235], v190 offset:1024
	ds_read_b128 v[240:243], v190 offset:3072
	v_lshl_add_u64 v[190:191], s[22:23], 0, v[132:133]
	s_mov_b32 m0, s12
	v_lshl_add_u64 v[244:245], s[22:23], 0, v[128:129]
	global_load_lds_dwordx4 v132, s[22:23]
	s_add_i32 m0, s12, 0x2000
	s_nop 0
	global_load_lds_dwordx4 v128, s[22:23]
	s_waitcnt vmcnt(10)
	s_barrier
	s_waitcnt lgkmcnt(2)
	v_mfma_f32_16x16x32_bf16 v[112:115], v[228:231], v[170:173], v[112:115]
	v_mfma_f32_16x16x32_bf16 v[104:107], v[236:239], v[170:173], v[104:107]
	v_mfma_f32_16x16x32_bf16 v[96:99], v[228:231], v[178:181], v[96:99]
	v_mfma_f32_16x16x32_bf16 v[88:91], v[236:239], v[178:181], v[88:91]
	v_mfma_f32_16x16x32_bf16 v[80:83], v[228:231], v[186:189], v[80:83]
	v_mfma_f32_16x16x32_bf16 v[72:75], v[236:239], v[186:189], v[72:75]
	v_mfma_f32_16x16x32_bf16 v[68:71], v[228:231], v[220:223], v[68:71]
	v_mfma_f32_16x16x32_bf16 v[64:67], v[236:239], v[220:223], v[64:67]
	s_waitcnt lgkmcnt(0)
	v_mfma_f32_16x16x32_bf16 v[112:115], v[232:235], v[174:177], v[112:115]
	v_mfma_f32_16x16x32_bf16 v[104:107], v[240:243], v[174:177], v[104:107]
	v_mfma_f32_16x16x32_bf16 v[96:99], v[232:235], v[182:185], v[96:99]
	v_mfma_f32_16x16x32_bf16 v[88:91], v[240:243], v[182:185], v[88:91]
	v_mfma_f32_16x16x32_bf16 v[80:83], v[232:235], v[216:219], v[80:83]
	v_mfma_f32_16x16x32_bf16 v[72:75], v[240:243], v[216:219], v[72:75]
	v_mfma_f32_16x16x32_bf16 v[68:71], v[232:235], v[224:227], v[68:71]
	v_mfma_f32_16x16x32_bf16 v[64:67], v[240:243], v[224:227], v[64:67]
	s_mov_b32 m0, s3
	s_barrier
	ds_read_b128 v[170:173], v153 offset:16384
	ds_read_b128 v[178:181], v153 offset:18432
	ds_read_b128 v[186:189], v153 offset:20480
	ds_read_b128 v[220:223], v153 offset:22528
	ds_read_b128 v[174:177], v153 offset:17408
	ds_read_b128 v[182:185], v153 offset:19456
	ds_read_b128 v[216:219], v153 offset:21504
	ds_read_b128 v[224:227], v153 offset:23552
	global_load_lds_dwordx4 v132, s[18:19]
	s_mov_b32 m0, s5
	s_nop 0
	global_load_lds_dwordx4 v128, s[18:19]
	s_waitcnt vmcnt(10)
	s_barrier
	s_waitcnt lgkmcnt(4)
	v_mfma_f32_16x16x32_bf16 v[60:63], v[154:157], v[170:173], v[60:63]
	v_mfma_f32_16x16x32_bf16 v[56:59], v[162:165], v[170:173], v[56:59]
	v_mfma_f32_16x16x32_bf16 v[52:55], v[154:157], v[178:181], v[52:55]
	v_mfma_f32_16x16x32_bf16 v[44:47], v[162:165], v[178:181], v[44:47]
	v_mfma_f32_16x16x32_bf16 v[36:39], v[154:157], v[186:189], v[36:39]
	v_mfma_f32_16x16x32_bf16 v[28:31], v[162:165], v[186:189], v[28:31]
	v_mfma_f32_16x16x32_bf16 v[20:23], v[154:157], v[220:223], v[20:23]
	v_mfma_f32_16x16x32_bf16 v[12:15], v[162:165], v[220:223], v[12:15]
	s_waitcnt lgkmcnt(0)
	v_mfma_f32_16x16x32_bf16 v[60:63], v[158:161], v[174:177], v[60:63]
	v_mfma_f32_16x16x32_bf16 v[56:59], v[166:169], v[174:177], v[56:59]
	v_mfma_f32_16x16x32_bf16 v[52:55], v[158:161], v[182:185], v[52:55]
	v_mfma_f32_16x16x32_bf16 v[44:47], v[166:169], v[182:185], v[44:47]
	v_mfma_f32_16x16x32_bf16 v[36:39], v[158:161], v[216:219], v[36:39]
	v_mfma_f32_16x16x32_bf16 v[28:31], v[166:169], v[216:219], v[28:31]
	v_mfma_f32_16x16x32_bf16 v[20:23], v[158:161], v[224:227], v[20:23]
	v_mfma_f32_16x16x32_bf16 v[12:15], v[166:169], v[224:227], v[12:15]
	s_barrier
	s_add_u32 s12, s22, s25
	s_addc_u32 s13, s23, 0
	s_add_i32 s22, s37, s26
	v_lshl_add_u64 v[250:251], s[12:13], 0, v[132:133]
	s_mov_b32 m0, s22
	v_lshl_add_u64 v[252:253], s[12:13], 0, v[128:129]
	global_load_lds_dwordx4 v132, s[12:13]
	s_add_i32 m0, s22, 0x2000
	s_nop 0
	global_load_lds_dwordx4 v128, s[12:13]
	v_add_u32_e32 v166, 0x18000, v152
	ds_read_b128 v[154:157], v166
	ds_read_b128 v[158:161], v166 offset:1024
	ds_read_b128 v[162:165], v166 offset:2048
	ds_read_b128 v[166:169], v166 offset:3072
	s_waitcnt vmcnt(10)
	s_barrier
	v_mfma_f32_16x16x32_bf16 v[48:51], v[228:231], v[170:173], v[48:51]
	v_mfma_f32_16x16x32_bf16 v[40:43], v[236:239], v[170:173], v[40:43]
	v_mfma_f32_16x16x32_bf16 v[32:35], v[228:231], v[178:181], v[32:35]
	v_mfma_f32_16x16x32_bf16 v[24:27], v[236:239], v[178:181], v[24:27]
	v_mfma_f32_16x16x32_bf16 v[16:19], v[228:231], v[186:189], v[16:19]
	v_mfma_f32_16x16x32_bf16 v[8:11], v[236:239], v[186:189], v[8:11]
	v_mfma_f32_16x16x32_bf16 v[4:7], v[228:231], v[220:223], v[4:7]
	v_mfma_f32_16x16x32_bf16 v[0:3], v[236:239], v[220:223], v[0:3]
	v_mfma_f32_16x16x32_bf16 v[48:51], v[232:235], v[174:177], v[48:51]
	v_mfma_f32_16x16x32_bf16 v[40:43], v[240:243], v[174:177], v[40:43]
	v_mfma_f32_16x16x32_bf16 v[32:35], v[232:235], v[182:185], v[32:35]
	v_mfma_f32_16x16x32_bf16 v[24:27], v[240:243], v[182:185], v[24:27]
	v_mfma_f32_16x16x32_bf16 v[16:19], v[232:235], v[216:219], v[16:19]
	v_mfma_f32_16x16x32_bf16 v[8:11], v[240:243], v[216:219], v[8:11]
	v_mfma_f32_16x16x32_bf16 v[4:7], v[232:235], v[224:227], v[4:7]
	v_mfma_f32_16x16x32_bf16 v[0:3], v[240:243], v[224:227], v[0:3]
	s_add_i32 s22, 0, 0x18000
	s_barrier
	s_add_u32 s12, s18, s25
	s_addc_u32 s13, s19, 0
	s_mov_b32 m0, s27
	ds_read_b128 v[170:173], v153 offset:32768
	ds_read_b128 v[178:181], v153 offset:34816
	ds_read_b128 v[186:189], v153 offset:36864
	ds_read_b128 v[220:223], v153 offset:38912
	ds_read_b128 v[174:177], v153 offset:33792
	ds_read_b128 v[182:185], v153 offset:35840
	ds_read_b128 v[216:219], v153 offset:37888
	ds_read_b128 v[224:227], v153 offset:39936
	global_load_lds_dwordx4 v132, s[12:13]
	s_mov_b32 m0, s28
	s_nop 0
	global_load_lds_dwordx4 v128, s[12:13]
	s_waitcnt lgkmcnt(8)
	s_waitcnt vmcnt(10)
	s_barrier
	s_waitcnt lgkmcnt(4)
	v_mfma_f32_16x16x32_bf16 v[124:127], v[154:157], v[170:173], v[124:127]
	v_mfma_f32_16x16x32_bf16 v[120:123], v[162:165], v[170:173], v[120:123]
	v_mfma_f32_16x16x32_bf16 v[116:119], v[154:157], v[178:181], v[116:119]
	v_mfma_f32_16x16x32_bf16 v[108:111], v[162:165], v[178:181], v[108:111]
	v_mfma_f32_16x16x32_bf16 v[100:103], v[154:157], v[186:189], v[100:103]
	v_mfma_f32_16x16x32_bf16 v[92:95], v[162:165], v[186:189], v[92:95]
	v_mfma_f32_16x16x32_bf16 v[84:87], v[154:157], v[220:223], v[84:87]
	v_mfma_f32_16x16x32_bf16 v[76:79], v[162:165], v[220:223], v[76:79]
	s_waitcnt lgkmcnt(0)
	v_mfma_f32_16x16x32_bf16 v[124:127], v[158:161], v[174:177], v[124:127]
	v_mfma_f32_16x16x32_bf16 v[120:123], v[166:169], v[174:177], v[120:123]
	v_mfma_f32_16x16x32_bf16 v[116:119], v[158:161], v[182:185], v[116:119]
	v_mfma_f32_16x16x32_bf16 v[108:111], v[166:169], v[182:185], v[108:111]
	v_mfma_f32_16x16x32_bf16 v[100:103], v[158:161], v[216:219], v[100:103]
	v_mfma_f32_16x16x32_bf16 v[92:95], v[166:169], v[216:219], v[92:95]
	v_mfma_f32_16x16x32_bf16 v[84:87], v[158:161], v[224:227], v[84:87]
	v_mfma_f32_16x16x32_bf16 v[76:79], v[166:169], v[224:227], v[76:79]
	s_barrier
	s_add_i32 s12, 0, 0x1c000
	s_add_i32 s13, s22, s26
	v_add_u32_e32 v200, s12, v152
	v_lshl_add_u64 v[190:191], v[190:191], 0, s[66:67]
	s_mov_b32 m0, s13
	ds_read_b128 v[228:231], v200
	ds_read_b128 v[236:239], v200 offset:2048
	ds_read_b128 v[232:235], v200 offset:1024
	ds_read_b128 v[240:243], v200 offset:3072
	global_load_lds_dwordx4 v[190:191], off
	v_lshl_add_u64 v[190:191], v[244:245], 0, s[66:67]
	s_add_i32 m0, s13, 0x2000
	s_nop 0
	global_load_lds_dwordx4 v[190:191], off
	s_waitcnt vmcnt(10)
	s_barrier
	s_waitcnt lgkmcnt(2)
	v_mfma_f32_16x16x32_bf16 v[112:115], v[228:231], v[170:173], v[112:115]
	v_mfma_f32_16x16x32_bf16 v[104:107], v[236:239], v[170:173], v[104:107]
	v_mfma_f32_16x16x32_bf16 v[96:99], v[228:231], v[178:181], v[96:99]
	v_mfma_f32_16x16x32_bf16 v[88:91], v[236:239], v[178:181], v[88:91]
	v_mfma_f32_16x16x32_bf16 v[80:83], v[228:231], v[186:189], v[80:83]
	v_mfma_f32_16x16x32_bf16 v[72:75], v[236:239], v[186:189], v[72:75]
	v_mfma_f32_16x16x32_bf16 v[68:71], v[228:231], v[220:223], v[68:71]
	v_mfma_f32_16x16x32_bf16 v[64:67], v[236:239], v[220:223], v[64:67]
	s_waitcnt lgkmcnt(0)
	v_mfma_f32_16x16x32_bf16 v[112:115], v[232:235], v[174:177], v[112:115]
	v_mfma_f32_16x16x32_bf16 v[104:107], v[240:243], v[174:177], v[104:107]
	v_mfma_f32_16x16x32_bf16 v[96:99], v[232:235], v[182:185], v[96:99]
	v_mfma_f32_16x16x32_bf16 v[88:91], v[240:243], v[182:185], v[88:91]
	v_mfma_f32_16x16x32_bf16 v[80:83], v[232:235], v[216:219], v[80:83]
	v_mfma_f32_16x16x32_bf16 v[72:75], v[240:243], v[216:219], v[72:75]
	v_mfma_f32_16x16x32_bf16 v[68:71], v[232:235], v[224:227], v[68:71]
	v_mfma_f32_16x16x32_bf16 v[64:67], v[240:243], v[224:227], v[64:67]
	s_mov_b32 m0, s30
	s_barrier
	ds_read_b128 v[170:173], v153 offset:49152
	ds_read_b128 v[178:181], v153 offset:51200
	ds_read_b128 v[186:189], v153 offset:53248
	ds_read_b128 v[220:223], v153 offset:55296
	ds_read_b128 v[174:177], v153 offset:50176
	ds_read_b128 v[182:185], v153 offset:52224
	ds_read_b128 v[216:219], v153 offset:54272
	ds_read_b128 v[224:227], v153 offset:56320
	s_add_u32 s98, s18, 0x80
	s_addc_u32 s99, s19, 0
	global_load_lds_dwordx4 v132, s[98:99]
	s_mov_b32 m0, s31
	s_nop 0
	global_load_lds_dwordx4 v128, s[98:99]
	s_waitcnt vmcnt(10)
	s_barrier
	s_waitcnt lgkmcnt(4)
	v_mfma_f32_16x16x32_bf16 v[60:63], v[154:157], v[170:173], v[60:63]
	v_mfma_f32_16x16x32_bf16 v[56:59], v[162:165], v[170:173], v[56:59]
	v_mfma_f32_16x16x32_bf16 v[52:55], v[154:157], v[178:181], v[52:55]
	v_mfma_f32_16x16x32_bf16 v[44:47], v[162:165], v[178:181], v[44:47]
	v_mfma_f32_16x16x32_bf16 v[36:39], v[154:157], v[186:189], v[36:39]
	v_mfma_f32_16x16x32_bf16 v[28:31], v[162:165], v[186:189], v[28:31]
	v_mfma_f32_16x16x32_bf16 v[20:23], v[154:157], v[220:223], v[20:23]
	v_mfma_f32_16x16x32_bf16 v[12:15], v[162:165], v[220:223], v[12:15]
	s_waitcnt lgkmcnt(0)
	v_mfma_f32_16x16x32_bf16 v[60:63], v[158:161], v[174:177], v[60:63]
	v_mfma_f32_16x16x32_bf16 v[56:59], v[166:169], v[174:177], v[56:59]
	v_mfma_f32_16x16x32_bf16 v[52:55], v[158:161], v[182:185], v[52:55]
	v_mfma_f32_16x16x32_bf16 v[44:47], v[166:169], v[182:185], v[44:47]
	v_mfma_f32_16x16x32_bf16 v[36:39], v[158:161], v[216:219], v[36:39]
	v_mfma_f32_16x16x32_bf16 v[28:31], v[166:169], v[216:219], v[28:31]
	v_mfma_f32_16x16x32_bf16 v[20:23], v[158:161], v[224:227], v[20:23]
	v_mfma_f32_16x16x32_bf16 v[12:15], v[166:169], v[224:227], v[12:15]
	s_barrier
	s_add_i32 s12, s12, s26
	v_lshl_add_u64 v[154:155], v[250:251], 0, s[66:67]
	s_mov_b32 m0, s12
	s_nop 0
	global_load_lds_dwordx4 v[154:155], off
	v_lshl_add_u64 v[154:155], v[252:253], 0, s[66:67]
	s_add_i32 m0, s12, 0x2000
	s_nop 0
	global_load_lds_dwordx4 v[154:155], off
	v_add_u32_e32 v166, 0x10000, v152
	ds_read_b128 v[154:157], v166
	ds_read_b128 v[158:161], v166 offset:1024
	ds_read_b128 v[162:165], v166 offset:2048
	ds_read_b128 v[166:169], v166 offset:3072
	s_waitcnt vmcnt(10)
	s_barrier
	v_mfma_f32_16x16x32_bf16 v[48:51], v[228:231], v[170:173], v[48:51]
	v_mfma_f32_16x16x32_bf16 v[40:43], v[236:239], v[170:173], v[40:43]
	v_mfma_f32_16x16x32_bf16 v[32:35], v[228:231], v[178:181], v[32:35]
	v_mfma_f32_16x16x32_bf16 v[24:27], v[236:239], v[178:181], v[24:27]
	v_mfma_f32_16x16x32_bf16 v[16:19], v[228:231], v[186:189], v[16:19]
	v_mfma_f32_16x16x32_bf16 v[8:11], v[236:239], v[186:189], v[8:11]
	v_mfma_f32_16x16x32_bf16 v[4:7], v[228:231], v[220:223], v[4:7]
	v_mfma_f32_16x16x32_bf16 v[0:3], v[236:239], v[220:223], v[0:3]
	v_mfma_f32_16x16x32_bf16 v[48:51], v[232:235], v[174:177], v[48:51]
	v_mfma_f32_16x16x32_bf16 v[40:43], v[240:243], v[174:177], v[40:43]
	v_mfma_f32_16x16x32_bf16 v[32:35], v[232:235], v[182:185], v[32:35]
	v_mfma_f32_16x16x32_bf16 v[24:27], v[240:243], v[182:185], v[24:27]
	v_mfma_f32_16x16x32_bf16 v[16:19], v[232:235], v[216:219], v[16:19]
	v_mfma_f32_16x16x32_bf16 v[8:11], v[240:243], v[216:219], v[8:11]
	v_mfma_f32_16x16x32_bf16 v[4:7], v[232:235], v[224:227], v[4:7]
	v_mfma_f32_16x16x32_bf16 v[0:3], v[240:243], v[224:227], v[0:3]
	s_cmp_ge_u32 s35, s29
	s_mov_b64 s[12:13], s[16:17]
	s_mov_b32 s18, s35
	s_barrier
	s_cbranch_scc0 .LBB0_70
	s_waitcnt lgkmcnt(0)
	s_and_b64 s[6:7], s[6:7], exec
	v_mov_b32_e32 v128, v135
	s_mov_b64 s[6:7], s[0:1]
	s_load_dwordx2 s[6:7], s[6:7], 0x88
	s_cselect_b32 s3, 0x2000, 0
	v_readfirstlane_b32 s5, v128
	v_lshrrev_b32_e32 v129, 2, v128
	v_cvt_pk_bf16_f32 v104, v104, v105
	s_waitcnt lgkmcnt(0)
	s_add_u32 s6, s6, 0xfea4400
	s_addc_u32 s7, s7, 0
	s_ashr_i32 s8, s5, 2
	s_andn2_b32 s8, s8, 63
	v_and_or_b32 v128, v128, 15, s8
	s_lshr_b32 s5, s5, 1
	v_lshl_add_u32 v150, s2, 8, v128
	s_lshl_b32 s2, s4, s15
	s_and_b32 s5, s5, 0x60
	s_add_i32 s2, s2, s3
	v_and_or_b32 v132, v129, 12, s5
	v_add_u32_e32 v130, s2, v150
	v_mov_b64_e32 v[128:129], s[6:7]
	v_mad_i64_i32 v[130:131], s[4:5], v130, s96, v[128:129]
	s_lshl_b32 s58, s58, 9
	v_lshl_add_u64 v[130:131], v[130:131], 0, s[58:59]
	v_lshlrev_b32_e32 v132, 1, v132
	v_lshl_add_u64 v[130:131], v[130:131], 0, v[132:133]
	v_cvt_pk_bf16_f32 v105, v106, v107
	global_store_dwordx2 v[130:131], v[104:105], off offset:1824
	v_add3_u32 v104, s2, 16, v150
	v_mad_i64_i32 v[104:105], s[4:5], v104, s96, v[128:129]
	v_lshl_add_u64 v[104:105], v[104:105], 0, s[58:59]
	v_lshl_add_u64 v[104:105], v[104:105], 0, v[132:133]
	v_cvt_pk_bf16_f32 v88, v88, v89
	v_cvt_pk_bf16_f32 v89, v90, v91
	global_store_dwordx2 v[104:105], v[88:89], off offset:1824
	v_add3_u32 v88, s2, 32, v150
	v_mad_i64_i32 v[88:89], s[4:5], v88, s96, v[128:129]
	v_lshl_add_u64 v[88:89], v[88:89], 0, s[58:59]
	v_lshl_add_u64 v[88:89], v[88:89], 0, v[132:133]
	v_cvt_pk_bf16_f32 v72, v72, v73
	v_cvt_pk_bf16_f32 v73, v74, v75
	global_store_dwordx2 v[88:89], v[72:73], off offset:1824
	v_add3_u32 v72, s2, 48, v150
	v_mad_i64_i32 v[72:73], s[4:5], v72, s96, v[128:129]
	v_lshl_add_u64 v[72:73], v[72:73], 0, s[58:59]
	v_lshl_add_u64 v[72:73], v[72:73], 0, v[132:133]
	v_cvt_pk_bf16_f32 v64, v64, v65
	s_add_i32 s3, s2, 0x80
	v_cvt_pk_bf16_f32 v65, v66, v67
	global_store_dwordx2 v[72:73], v[64:65], off offset:1824
	v_add_u32_e32 v64, s3, v150
	v_mad_i64_i32 v[64:65], s[4:5], v64, s96, v[128:129]
	v_lshl_add_u64 v[64:65], v[64:65], 0, s[58:59]
	v_lshl_add_u64 v[64:65], v[64:65], 0, v[132:133]
	v_cvt_pk_bf16_f32 v40, v40, v41
	s_add_i32 s3, s2, 0x90
	v_cvt_pk_bf16_f32 v41, v42, v43
	global_store_dwordx2 v[64:65], v[40:41], off offset:1824
	v_add_u32_e32 v40, s3, v150
	v_mad_i64_i32 v[40:41], s[4:5], v40, s96, v[128:129]
	v_lshl_add_u64 v[40:41], v[40:41], 0, s[58:59]
	v_lshl_add_u64 v[40:41], v[40:41], 0, v[132:133]
	v_cvt_pk_bf16_f32 v24, v24, v25
	s_add_i32 s3, s2, 0xa0
	v_cvt_pk_bf16_f32 v25, v26, v27
	global_store_dwordx2 v[40:41], v[24:25], off offset:1824
	v_add_u32_e32 v24, s3, v150
	v_mad_i64_i32 v[24:25], s[4:5], v24, s96, v[128:129]
	v_lshl_add_u64 v[24:25], v[24:25], 0, s[58:59]
	v_lshl_add_u64 v[24:25], v[24:25], 0, v[132:133]
	v_cvt_pk_bf16_f32 v8, v8, v9
	s_addk_i32 s2, 0xb0
	v_cvt_pk_bf16_f32 v9, v10, v11
	global_store_dwordx2 v[24:25], v[8:9], off offset:1824
	v_add_u32_e32 v8, s2, v150
	v_mad_i64_i32 v[8:9], s[2:3], v8, s96, v[128:129]
	v_lshl_add_u64 v[8:9], v[8:9], 0, s[58:59]
	v_cvt_pk_bf16_f32 v106, v116, v117
	v_cvt_pk_bf16_f32 v107, v118, v119
	v_cvt_pk_bf16_f32 v90, v100, v101
	v_cvt_pk_bf16_f32 v91, v102, v103
	v_cvt_pk_bf16_f32 v74, v84, v85
	v_cvt_pk_bf16_f32 v75, v86, v87
	v_cvt_pk_bf16_f32 v42, v52, v53
	v_cvt_pk_bf16_f32 v43, v54, v55
	v_cvt_pk_bf16_f32 v26, v36, v37
	v_cvt_pk_bf16_f32 v27, v38, v39
	v_lshl_add_u64 v[8:9], v[8:9], 0, v[132:133]
	v_cvt_pk_bf16_f32 v10, v20, v21
	v_cvt_pk_bf16_f32 v11, v22, v23
	v_cvt_pk_bf16_f32 v124, v124, v125
	v_cvt_pk_bf16_f32 v125, v126, v127
	global_store_dwordx2 v[130:131], v[124:125], off offset:1536
	v_cvt_pk_bf16_f32 v120, v120, v121
	v_cvt_pk_bf16_f32 v121, v122, v123
	global_store_dwordx2 v[130:131], v[120:121], off offset:1568
	v_cvt_pk_bf16_f32 v112, v112, v113
	v_cvt_pk_bf16_f32 v113, v114, v115
	global_store_dwordx2 v[130:131], v[112:113], off offset:1792
	global_store_dwordx2 v[104:105], v[106:107], off offset:1536
	v_cvt_pk_bf16_f32 v106, v108, v109
	v_cvt_pk_bf16_f32 v107, v110, v111
	global_store_dwordx2 v[104:105], v[106:107], off offset:1568
	v_cvt_pk_bf16_f32 v96, v96, v97
	v_cvt_pk_bf16_f32 v97, v98, v99
	global_store_dwordx2 v[104:105], v[96:97], off offset:1792
	global_store_dwordx2 v[88:89], v[90:91], off offset:1536
	v_cvt_pk_bf16_f32 v90, v92, v93
	v_cvt_pk_bf16_f32 v91, v94, v95
	global_store_dwordx2 v[88:89], v[90:91], off offset:1568
	v_cvt_pk_bf16_f32 v80, v80, v81
	v_cvt_pk_bf16_f32 v81, v82, v83
	global_store_dwordx2 v[88:89], v[80:81], off offset:1792
	global_store_dwordx2 v[72:73], v[74:75], off offset:1536
	v_cvt_pk_bf16_f32 v74, v76, v77
	v_cvt_pk_bf16_f32 v75, v78, v79
	global_store_dwordx2 v[72:73], v[74:75], off offset:1568
	v_cvt_pk_bf16_f32 v68, v68, v69
	v_cvt_pk_bf16_f32 v69, v70, v71
	global_store_dwordx2 v[72:73], v[68:69], off offset:1792
	v_cvt_pk_bf16_f32 v60, v60, v61
	v_cvt_pk_bf16_f32 v61, v62, v63
	global_store_dwordx2 v[64:65], v[60:61], off offset:1536
	v_cvt_pk_bf16_f32 v56, v56, v57
	v_cvt_pk_bf16_f32 v57, v58, v59
	global_store_dwordx2 v[64:65], v[56:57], off offset:1568
	v_cvt_pk_bf16_f32 v48, v48, v49
	v_cvt_pk_bf16_f32 v49, v50, v51
	global_store_dwordx2 v[64:65], v[48:49], off offset:1792
	global_store_dwordx2 v[40:41], v[42:43], off offset:1536
	v_cvt_pk_bf16_f32 v42, v44, v45
	v_cvt_pk_bf16_f32 v43, v46, v47
	global_store_dwordx2 v[40:41], v[42:43], off offset:1568
	v_cvt_pk_bf16_f32 v32, v32, v33
	v_cvt_pk_bf16_f32 v33, v34, v35
	global_store_dwordx2 v[40:41], v[32:33], off offset:1792
	global_store_dwordx2 v[24:25], v[26:27], off offset:1536
	v_cvt_pk_bf16_f32 v26, v28, v29
	v_cvt_pk_bf16_f32 v27, v30, v31
	global_store_dwordx2 v[24:25], v[26:27], off offset:1568
	v_cvt_pk_bf16_f32 v16, v16, v17
	v_cvt_pk_bf16_f32 v17, v18, v19
	global_store_dwordx2 v[24:25], v[16:17], off offset:1792
	global_store_dwordx2 v[8:9], v[10:11], off offset:1536
	v_cvt_pk_bf16_f32 v10, v12, v13
	v_cvt_pk_bf16_f32 v11, v14, v15
	global_store_dwordx2 v[8:9], v[10:11], off offset:1568
	v_cvt_pk_bf16_f32 v4, v4, v5
	v_cvt_pk_bf16_f32 v5, v6, v7
	global_store_dwordx2 v[8:9], v[4:5], off offset:1792
	v_cvt_pk_bf16_f32 v0, v0, v1
	v_cvt_pk_bf16_f32 v1, v2, v3
	global_store_dwordx2 v[8:9], v[0:1], off offset:1824
	s_waitcnt vmcnt(0)
	s_cmpk_lt_u32 s14, 0x100
	s_cbranch_scc0 .LBB0_73
	s_barrier

.LBB0_145:
	s_add_u32 s6, s2, 0xfffc0080
	s_addc_u32 s7, s3, -1
	s_add_i32 s29, 0, 0x10000
	s_cmp_eq_u32 s28, 12
	s_cselect_b32 s11, s9, s7
	s_cselect_b32 s10, s12, s6
	s_cselect_b32 s7, s13, s27
	s_cselect_b32 s6, s17, s19
	s_add_i32 m0, s50, 0xc000
	ds_read_b128 v[170:173], v216
	ds_read_b128 v[178:181], v216 offset:2048
	ds_read_b128 v[186:189], v216 offset:4096
	ds_read_b128 v[222:225], v216 offset:6144
	ds_read_b128 v[174:177], v216 offset:1024
	ds_read_b128 v[182:185], v216 offset:3072
	ds_read_b128 v[218:221], v216 offset:5120
	ds_read_b128 v[226:229], v216 offset:7168
	global_load_lds_dwordx4 v154, s[2:3]
	s_add_i32 m0, s50, 0xe000
	s_nop 0
	global_load_lds_dwordx4 v156, s[2:3]
	s_waitcnt lgkmcnt(8)
	s_waitcnt vmcnt(10)
	s_barrier
	s_waitcnt lgkmcnt(4)
	v_mfma_f32_16x16x32_bf16 v[124:127], v[128:131], v[170:173], v[124:127]
	v_mfma_f32_16x16x32_bf16 v[120:123], v[162:165], v[170:173], v[120:123]
	v_mfma_f32_16x16x32_bf16 v[108:111], v[128:131], v[178:181], v[108:111]
	v_mfma_f32_16x16x32_bf16 v[104:107], v[162:165], v[178:181], v[104:107]
	v_mfma_f32_16x16x32_bf16 v[92:95], v[128:131], v[186:189], v[92:95]
	v_mfma_f32_16x16x32_bf16 v[88:91], v[162:165], v[186:189], v[88:91]
	v_mfma_f32_16x16x32_bf16 v[76:79], v[128:131], v[222:225], v[76:79]
	v_mfma_f32_16x16x32_bf16 v[72:75], v[162:165], v[222:225], v[72:75]
	s_waitcnt lgkmcnt(0)
	v_mfma_f32_16x16x32_bf16 v[124:127], v[158:161], v[174:177], v[124:127]
	v_mfma_f32_16x16x32_bf16 v[120:123], v[166:169], v[174:177], v[120:123]
	v_mfma_f32_16x16x32_bf16 v[108:111], v[158:161], v[182:185], v[108:111]
	v_mfma_f32_16x16x32_bf16 v[104:107], v[166:169], v[182:185], v[104:107]
	v_mfma_f32_16x16x32_bf16 v[92:95], v[158:161], v[218:221], v[92:95]
	v_mfma_f32_16x16x32_bf16 v[88:91], v[166:169], v[218:221], v[88:91]
	v_mfma_f32_16x16x32_bf16 v[76:79], v[158:161], v[226:229], v[76:79]
	v_mfma_f32_16x16x32_bf16 v[72:75], v[166:169], v[226:229], v[72:75]
	s_barrier
	s_add_i32 s34, 0, 0x14000
	s_add_i32 s29, s29, s15
	v_add_u32_e32 v132, s34, v215
	s_mov_b32 m0, s29
	ds_read_b128 v[230:233], v132
	ds_read_b128 v[238:241], v132 offset:2048
	ds_read_b128 v[234:237], v132 offset:1024
	ds_read_b128 v[242:245], v132 offset:3072
	global_load_lds_dwordx4 v150, s[6:7]
	s_add_i32 m0, s29, 0x2000
	s_nop 0
	global_load_lds_dwordx4 v152, s[6:7]
	s_waitcnt vmcnt(10)
	s_barrier
	s_waitcnt lgkmcnt(2)
	v_mfma_f32_16x16x32_bf16 v[116:119], v[230:233], v[170:173], v[116:119]
	v_mfma_f32_16x16x32_bf16 v[112:115], v[238:241], v[170:173], v[112:115]
	v_mfma_f32_16x16x32_bf16 v[100:103], v[230:233], v[178:181], v[100:103]
	v_mfma_f32_16x16x32_bf16 v[96:99], v[238:241], v[178:181], v[96:99]
	v_mfma_f32_16x16x32_bf16 v[84:87], v[230:233], v[186:189], v[84:87]
	v_mfma_f32_16x16x32_bf16 v[80:83], v[238:241], v[186:189], v[80:83]
	v_mfma_f32_16x16x32_bf16 v[68:71], v[230:233], v[222:225], v[68:71]
	v_mfma_f32_16x16x32_bf16 v[64:67], v[238:241], v[222:225], v[64:67]
	s_waitcnt lgkmcnt(0)
	v_mfma_f32_16x16x32_bf16 v[116:119], v[234:237], v[174:177], v[116:119]
	v_mfma_f32_16x16x32_bf16 v[112:115], v[242:245], v[174:177], v[112:115]
	v_mfma_f32_16x16x32_bf16 v[100:103], v[234:237], v[182:185], v[100:103]
	v_mfma_f32_16x16x32_bf16 v[96:99], v[242:245], v[182:185], v[96:99]
	v_mfma_f32_16x16x32_bf16 v[84:87], v[234:237], v[218:221], v[84:87]
	v_mfma_f32_16x16x32_bf16 v[80:83], v[242:245], v[218:221], v[80:83]
	v_mfma_f32_16x16x32_bf16 v[68:71], v[234:237], v[226:229], v[68:71]
	v_mfma_f32_16x16x32_bf16 v[64:67], v[242:245], v[226:229], v[64:67]
	s_mov_b32 m0, s50
	v_lshl_add_u64 v[248:249], s[10:11], 0, v[150:151]
	s_barrier
	ds_read_b128 v[170:173], v216 offset:16384
	ds_read_b128 v[178:181], v216 offset:18432
	ds_read_b128 v[186:189], v216 offset:20480
	ds_read_b128 v[222:225], v216 offset:22528
	ds_read_b128 v[174:177], v216 offset:17408
	ds_read_b128 v[182:185], v216 offset:19456
	ds_read_b128 v[218:221], v216 offset:21504
	ds_read_b128 v[226:229], v216 offset:23552
	global_load_lds_dwordx4 v150, s[10:11]
	v_lshl_add_u64 v[250:251], s[10:11], 0, v[152:153]
	s_mov_b32 m0, s51
	s_nop 0
	global_load_lds_dwordx4 v152, s[10:11]
	s_waitcnt vmcnt(10)
	s_barrier
	s_waitcnt lgkmcnt(4)
	v_mfma_f32_16x16x32_bf16 v[60:63], v[128:131], v[170:173], v[60:63]
	v_mfma_f32_16x16x32_bf16 v[56:59], v[162:165], v[170:173], v[56:59]
	v_mfma_f32_16x16x32_bf16 v[44:47], v[128:131], v[178:181], v[44:47]
	v_mfma_f32_16x16x32_bf16 v[40:43], v[162:165], v[178:181], v[40:43]
	v_mfma_f32_16x16x32_bf16 v[28:31], v[128:131], v[186:189], v[28:31]
	v_mfma_f32_16x16x32_bf16 v[24:27], v[162:165], v[186:189], v[24:27]
	v_mfma_f32_16x16x32_bf16 v[12:15], v[128:131], v[222:225], v[12:15]
	v_mfma_f32_16x16x32_bf16 v[8:11], v[162:165], v[222:225], v[8:11]
	s_waitcnt lgkmcnt(0)
	v_mfma_f32_16x16x32_bf16 v[60:63], v[158:161], v[174:177], v[60:63]
	v_mfma_f32_16x16x32_bf16 v[56:59], v[166:169], v[174:177], v[56:59]
	v_mfma_f32_16x16x32_bf16 v[44:47], v[158:161], v[182:185], v[44:47]
	v_mfma_f32_16x16x32_bf16 v[40:43], v[166:169], v[182:185], v[40:43]
	v_mfma_f32_16x16x32_bf16 v[28:31], v[158:161], v[218:221], v[28:31]
	v_mfma_f32_16x16x32_bf16 v[24:27], v[166:169], v[218:221], v[24:27]
	v_mfma_f32_16x16x32_bf16 v[12:15], v[158:161], v[226:229], v[12:15]
	v_mfma_f32_16x16x32_bf16 v[8:11], v[166:169], v[226:229], v[8:11]
	s_barrier
	s_add_u32 s30, s6, 0x40000
	s_addc_u32 s31, s7, 0
	s_add_i32 s29, s34, s15
	s_mov_b32 m0, s29
	s_nop 0
	global_load_lds_dwordx4 v150, s[30:31]
	s_add_i32 m0, s29, 0x2000
	s_nop 0
	global_load_lds_dwordx4 v152, s[30:31]
	v_add_u32_e32 v166, 0x18000, v215
	ds_read_b128 v[128:131], v166
	ds_read_b128 v[158:161], v166 offset:1024
	ds_read_b128 v[162:165], v166 offset:2048
	ds_read_b128 v[166:169], v166 offset:3072
	s_waitcnt vmcnt(10)
	s_barrier
	v_mfma_f32_16x16x32_bf16 v[52:55], v[230:233], v[170:173], v[52:55]
	v_mfma_f32_16x16x32_bf16 v[48:51], v[238:241], v[170:173], v[48:51]
	v_mfma_f32_16x16x32_bf16 v[36:39], v[230:233], v[178:181], v[36:39]
	v_mfma_f32_16x16x32_bf16 v[32:35], v[238:241], v[178:181], v[32:35]
	v_mfma_f32_16x16x32_bf16 v[20:23], v[230:233], v[186:189], v[20:23]
	v_mfma_f32_16x16x32_bf16 v[16:19], v[238:241], v[186:189], v[16:19]
	v_mfma_f32_16x16x32_bf16 v[4:7], v[230:233], v[222:225], v[4:7]
	v_mfma_f32_16x16x32_bf16 v[0:3], v[238:241], v[222:225], v[0:3]
	v_mfma_f32_16x16x32_bf16 v[52:55], v[234:237], v[174:177], v[52:55]
	v_mfma_f32_16x16x32_bf16 v[48:51], v[242:245], v[174:177], v[48:51]
	v_mfma_f32_16x16x32_bf16 v[36:39], v[234:237], v[182:185], v[36:39]
	v_mfma_f32_16x16x32_bf16 v[32:35], v[242:245], v[182:185], v[32:35]
	v_mfma_f32_16x16x32_bf16 v[20:23], v[234:237], v[218:221], v[20:23]
	v_mfma_f32_16x16x32_bf16 v[16:19], v[242:245], v[218:221], v[16:19]
	v_mfma_f32_16x16x32_bf16 v[4:7], v[234:237], v[226:229], v[4:7]
	v_mfma_f32_16x16x32_bf16 v[0:3], v[242:245], v[226:229], v[0:3]
	s_add_i32 s29, 0, 0x18000
	s_barrier
	s_add_u32 s10, s10, 0x40000
	s_addc_u32 s11, s11, 0
	s_mov_b32 m0, s36
	ds_read_b128 v[170:173], v216 offset:32768
	ds_read_b128 v[178:181], v216 offset:34816
	ds_read_b128 v[186:189], v216 offset:36864
	ds_read_b128 v[222:225], v216 offset:38912
	ds_read_b128 v[174:177], v216 offset:33792
	ds_read_b128 v[182:185], v216 offset:35840
	ds_read_b128 v[218:221], v216 offset:37888
	ds_read_b128 v[226:229], v216 offset:39936
	global_load_lds_dwordx4 v150, s[10:11]
	s_mov_b32 m0, s37
	s_nop 0
	global_load_lds_dwordx4 v152, s[10:11]
	s_waitcnt lgkmcnt(8)
	s_waitcnt vmcnt(10)
	s_barrier
	s_waitcnt lgkmcnt(4)
	v_mfma_f32_16x16x32_bf16 v[124:127], v[128:131], v[170:173], v[124:127]
	v_mfma_f32_16x16x32_bf16 v[120:123], v[162:165], v[170:173], v[120:123]
	v_mfma_f32_16x16x32_bf16 v[108:111], v[128:131], v[178:181], v[108:111]
	v_mfma_f32_16x16x32_bf16 v[104:107], v[162:165], v[178:181], v[104:107]
	v_mfma_f32_16x16x32_bf16 v[92:95], v[128:131], v[186:189], v[92:95]
	v_mfma_f32_16x16x32_bf16 v[88:91], v[162:165], v[186:189], v[88:91]
	v_mfma_f32_16x16x32_bf16 v[76:79], v[128:131], v[222:225], v[76:79]
	v_mfma_f32_16x16x32_bf16 v[72:75], v[162:165], v[222:225], v[72:75]
	s_waitcnt lgkmcnt(0)
	v_mfma_f32_16x16x32_bf16 v[124:127], v[158:161], v[174:177], v[124:127]
	v_mfma_f32_16x16x32_bf16 v[120:123], v[166:169], v[174:177], v[120:123]
	v_mfma_f32_16x16x32_bf16 v[108:111], v[158:161], v[182:185], v[108:111]
	v_mfma_f32_16x16x32_bf16 v[104:107], v[166:169], v[182:185], v[104:107]
	v_mfma_f32_16x16x32_bf16 v[92:95], v[158:161], v[218:221], v[92:95]
	v_mfma_f32_16x16x32_bf16 v[88:91], v[166:169], v[218:221], v[88:91]
	v_mfma_f32_16x16x32_bf16 v[76:79], v[158:161], v[226:229], v[76:79]
	v_mfma_f32_16x16x32_bf16 v[72:75], v[166:169], v[226:229], v[72:75]
	s_barrier
	s_add_i32 s10, 0, 0x1c000
	s_add_i32 s11, s29, s15
	v_add_u32_e32 v132, s10, v215
	s_mov_b32 m0, s11
	ds_read_b128 v[230:233], v132
	ds_read_b128 v[238:241], v132 offset:2048
	ds_read_b128 v[234:237], v132 offset:1024
	ds_read_b128 v[242:245], v132 offset:3072
	s_add_u32 s98, s6, 0x80
	s_addc_u32 s99, s7, 0
	global_load_lds_dwordx4 v150, s[98:99]
	s_add_i32 m0, s11, 0x2000
	s_nop 0
	global_load_lds_dwordx4 v152, s[98:99]
	s_waitcnt vmcnt(10)
	s_barrier
	s_waitcnt lgkmcnt(2)
	v_mfma_f32_16x16x32_bf16 v[116:119], v[230:233], v[170:173], v[116:119]
	v_mfma_f32_16x16x32_bf16 v[112:115], v[238:241], v[170:173], v[112:115]
	v_mfma_f32_16x16x32_bf16 v[100:103], v[230:233], v[178:181], v[100:103]
	v_mfma_f32_16x16x32_bf16 v[96:99], v[238:241], v[178:181], v[96:99]
	v_mfma_f32_16x16x32_bf16 v[84:87], v[230:233], v[186:189], v[84:87]
	v_mfma_f32_16x16x32_bf16 v[80:83], v[238:241], v[186:189], v[80:83]
	v_mfma_f32_16x16x32_bf16 v[68:71], v[230:233], v[222:225], v[68:71]
	v_mfma_f32_16x16x32_bf16 v[64:67], v[238:241], v[222:225], v[64:67]
	s_waitcnt lgkmcnt(0)
	v_mfma_f32_16x16x32_bf16 v[116:119], v[234:237], v[174:177], v[116:119]
	v_mfma_f32_16x16x32_bf16 v[112:115], v[242:245], v[174:177], v[112:115]
	v_mfma_f32_16x16x32_bf16 v[100:103], v[234:237], v[182:185], v[100:103]
	v_mfma_f32_16x16x32_bf16 v[96:99], v[242:245], v[182:185], v[96:99]
	v_mfma_f32_16x16x32_bf16 v[84:87], v[234:237], v[218:221], v[84:87]
	v_mfma_f32_16x16x32_bf16 v[80:83], v[242:245], v[218:221], v[80:83]
	v_mfma_f32_16x16x32_bf16 v[68:71], v[234:237], v[226:229], v[68:71]
	v_mfma_f32_16x16x32_bf16 v[64:67], v[242:245], v[226:229], v[64:67]
	s_mov_b32 m0, s52
	v_lshl_add_u64 v[190:191], v[248:249], 0, s[66:67]
	s_barrier
	ds_read_b128 v[170:173], v216 offset:49152
	ds_read_b128 v[178:181], v216 offset:51200
	ds_read_b128 v[186:189], v216 offset:53248
	ds_read_b128 v[222:225], v216 offset:55296
	ds_read_b128 v[174:177], v216 offset:50176
	ds_read_b128 v[182:185], v216 offset:52224
	ds_read_b128 v[218:221], v216 offset:54272
	ds_read_b128 v[226:229], v216 offset:56320
	global_load_lds_dwordx4 v[190:191], off
	v_lshl_add_u64 v[190:191], v[250:251], 0, s[66:67]
	s_mov_b32 m0, s53
	s_nop 0
	global_load_lds_dwordx4 v[190:191], off
	s_waitcnt vmcnt(10)
	s_barrier
	s_waitcnt lgkmcnt(4)
	v_mfma_f32_16x16x32_bf16 v[60:63], v[128:131], v[170:173], v[60:63]
	v_mfma_f32_16x16x32_bf16 v[56:59], v[162:165], v[170:173], v[56:59]
	v_mfma_f32_16x16x32_bf16 v[44:47], v[128:131], v[178:181], v[44:47]
	v_mfma_f32_16x16x32_bf16 v[40:43], v[162:165], v[178:181], v[40:43]
	v_mfma_f32_16x16x32_bf16 v[28:31], v[128:131], v[186:189], v[28:31]
	v_mfma_f32_16x16x32_bf16 v[24:27], v[162:165], v[186:189], v[24:27]
	v_mfma_f32_16x16x32_bf16 v[12:15], v[128:131], v[222:225], v[12:15]
	v_mfma_f32_16x16x32_bf16 v[8:11], v[162:165], v[222:225], v[8:11]
	s_waitcnt lgkmcnt(0)
	v_mfma_f32_16x16x32_bf16 v[60:63], v[158:161], v[174:177], v[60:63]
	v_mfma_f32_16x16x32_bf16 v[56:59], v[166:169], v[174:177], v[56:59]
	v_mfma_f32_16x16x32_bf16 v[44:47], v[158:161], v[182:185], v[44:47]
	v_mfma_f32_16x16x32_bf16 v[40:43], v[166:169], v[182:185], v[40:43]
	v_mfma_f32_16x16x32_bf16 v[28:31], v[158:161], v[218:221], v[28:31]
	v_mfma_f32_16x16x32_bf16 v[24:27], v[166:169], v[218:221], v[24:27]
	v_mfma_f32_16x16x32_bf16 v[12:15], v[158:161], v[226:229], v[12:15]
	v_mfma_f32_16x16x32_bf16 v[8:11], v[166:169], v[226:229], v[8:11]
	s_barrier
	s_add_u32 s6, s6, 0x40080
	s_addc_u32 s7, s7, 0
	s_add_i32 s10, s10, s15
	s_mov_b32 m0, s10
	s_nop 0
	global_load_lds_dwordx4 v150, s[6:7]
	s_add_i32 m0, s10, 0x2000
	s_nop 0
	global_load_lds_dwordx4 v152, s[6:7]
	v_add_u32_e32 v166, 0x10000, v215
	ds_read_b128 v[128:131], v166
	ds_read_b128 v[158:161], v166 offset:1024
	ds_read_b128 v[162:165], v166 offset:2048
	ds_read_b128 v[166:169], v166 offset:3072
	s_waitcnt vmcnt(10)
	s_barrier
	v_mfma_f32_16x16x32_bf16 v[52:55], v[230:233], v[170:173], v[52:55]
	v_mfma_f32_16x16x32_bf16 v[48:51], v[238:241], v[170:173], v[48:51]
	v_mfma_f32_16x16x32_bf16 v[36:39], v[230:233], v[178:181], v[36:39]
	v_mfma_f32_16x16x32_bf16 v[32:35], v[238:241], v[178:181], v[32:35]
	v_mfma_f32_16x16x32_bf16 v[20:23], v[230:233], v[186:189], v[20:23]
	v_mfma_f32_16x16x32_bf16 v[16:19], v[238:241], v[186:189], v[16:19]
	v_mfma_f32_16x16x32_bf16 v[4:7], v[230:233], v[222:225], v[4:7]
	v_mfma_f32_16x16x32_bf16 v[0:3], v[238:241], v[222:225], v[0:3]
	v_mfma_f32_16x16x32_bf16 v[52:55], v[234:237], v[174:177], v[52:55]
	v_mfma_f32_16x16x32_bf16 v[48:51], v[242:245], v[174:177], v[48:51]
	v_mfma_f32_16x16x32_bf16 v[36:39], v[234:237], v[182:185], v[36:39]
	v_mfma_f32_16x16x32_bf16 v[32:35], v[242:245], v[182:185], v[32:35]
	v_mfma_f32_16x16x32_bf16 v[20:23], v[234:237], v[218:221], v[20:23]
	v_mfma_f32_16x16x32_bf16 v[16:19], v[242:245], v[218:221], v[16:19]
	v_mfma_f32_16x16x32_bf16 v[4:7], v[234:237], v[226:229], v[4:7]
	v_mfma_f32_16x16x32_bf16 v[0:3], v[242:245], v[226:229], v[0:3]
	s_add_i32 s28, s28, 2
	s_add_u32 s2, s2, 0x100
	s_addc_u32 s3, s3, 0
	s_add_u32 s19, s19, 0x100
	s_addc_u32 s27, s27, 0
	s_cmp_gt_u32 s28, 13
	s_barrier
	s_cbranch_scc0 .LBB0_145
	s_waitcnt lgkmcnt(0)
	v_mov_b32_e32 v166, v135
	s_mov_b64 s[2:3], s[0:1]
	v_readfirstlane_b32 s27, v166
	s_bfe_u32 s19, s27, 0x20006
	s_load_dwordx2 s[30:31], s[2:3], 0x88
	s_mov_b64 s[2:3], s[0:1]
	s_cmp_gt_i32 s8, 31
	s_load_dwordx2 s[28:29], s[2:3], 0x80
	s_cselect_b64 s[6:7], -1, 0
	s_cmp_lt_i32 s8, 32
	s_cselect_b64 s[2:3], -1, 0
	s_ashr_i32 s9, s27, 2
	s_lshl_b32 s8, s8, 8
	s_and_b32 s17, s9, 0xffffffc0
	v_and_b32_e32 v217, 15, v166
	s_add_i32 s17, s17, s8
	v_bfe_u32 v186, v166, 4, 2
	v_or_b32_e32 v158, s17, v217
	s_cmp_gt_i32 s26, 3
	s_mov_b64 s[8:9], -1
	s_cbranch_scc0 .LBB0_829
	s_cmp_gt_u32 s26, 5
	s_cbranch_scc0 .LBB0_409
	s_cmp_gt_u32 s26, 8
	s_cbranch_scc0 .LBB0_406
	s_waitcnt lgkmcnt(0)
	v_and_b32_e32 v128, 1, v166
	v_cmp_eq_u32_e64 s[8:9], 0, v128
	v_cmp_eq_u32_e32 vcc, 1, v128
	s_mov_b32 s10, 0x05040100
	s_mov_b32 s11, 0x07060302
	s_cmp_eq_u32 s6, 0
	s_cbranch_scc1 .Lvf_f_c

.LBB0_1104:
	s_add_u32 s22, s18, 0xfffc0080
	s_addc_u32 s23, s19, -1
	s_add_i32 s47, 0, 0x10000
	s_cmp_eq_u32 s46, 12
	s_cselect_b32 s25, s9, s23
	s_cselect_b32 s24, s42, s22
	s_cselect_b32 s23, s7, s45
	s_cselect_b32 s22, s43, s44
	s_add_i32 m0, s17, 0xc000
	ds_read_b128 v[172:175], v155
	ds_read_b128 v[180:183], v155 offset:2048
	ds_read_b128 v[188:191], v155 offset:4096
	ds_read_b128 v[220:223], v155 offset:6144
	ds_read_b128 v[176:179], v155 offset:1024
	ds_read_b128 v[184:187], v155 offset:3072
	ds_read_b128 v[216:219], v155 offset:5120
	ds_read_b128 v[224:227], v155 offset:7168
	global_load_lds_dwordx4 v130, s[18:19]
	s_add_i32 m0, s17, 0xe000
	s_nop 0
	global_load_lds_dwordx4 v150, s[18:19]
	s_waitcnt lgkmcnt(8)
	s_waitcnt vmcnt(10)
	s_barrier
	s_waitcnt lgkmcnt(4)
	v_mfma_f32_16x16x32_bf16 v[124:127], v[156:159], v[172:175], v[124:127]
	v_mfma_f32_16x16x32_bf16 v[120:123], v[164:167], v[172:175], v[120:123]
	v_mfma_f32_16x16x32_bf16 v[108:111], v[156:159], v[180:183], v[108:111]
	v_mfma_f32_16x16x32_bf16 v[104:107], v[164:167], v[180:183], v[104:107]
	v_mfma_f32_16x16x32_bf16 v[92:95], v[156:159], v[188:191], v[92:95]
	v_mfma_f32_16x16x32_bf16 v[88:91], v[164:167], v[188:191], v[88:91]
	v_mfma_f32_16x16x32_bf16 v[76:79], v[156:159], v[220:223], v[76:79]
	v_mfma_f32_16x16x32_bf16 v[72:75], v[164:167], v[220:223], v[72:75]
	s_waitcnt lgkmcnt(0)
	v_mfma_f32_16x16x32_bf16 v[124:127], v[160:163], v[176:179], v[124:127]
	v_mfma_f32_16x16x32_bf16 v[120:123], v[168:171], v[176:179], v[120:123]
	v_mfma_f32_16x16x32_bf16 v[108:111], v[160:163], v[184:187], v[108:111]
	v_mfma_f32_16x16x32_bf16 v[104:107], v[168:171], v[184:187], v[104:107]
	v_mfma_f32_16x16x32_bf16 v[92:95], v[160:163], v[216:219], v[92:95]
	v_mfma_f32_16x16x32_bf16 v[88:91], v[168:171], v[216:219], v[88:91]
	v_mfma_f32_16x16x32_bf16 v[76:79], v[160:163], v[224:227], v[76:79]
	v_mfma_f32_16x16x32_bf16 v[72:75], v[168:171], v[224:227], v[72:75]
	s_barrier
	s_add_i32 s50, 0, 0x14000
	v_add_u32_e32 v152, s50, v154
	s_add_i32 s47, s47, s29
	ds_read_b128 v[228:231], v152
	ds_read_b128 v[236:239], v152 offset:2048
	ds_read_b128 v[232:235], v152 offset:1024
	ds_read_b128 v[240:243], v152 offset:3072
	s_mov_b32 m0, s47
	s_nop 0
	global_load_lds_dwordx4 v132, s[22:23]
	s_add_i32 m0, s47, 0x2000
	s_nop 0
	global_load_lds_dwordx4 v128, s[22:23]
	s_waitcnt vmcnt(10)
	s_barrier
	s_waitcnt lgkmcnt(2)
	v_mfma_f32_16x16x32_bf16 v[116:119], v[228:231], v[172:175], v[116:119]
	v_mfma_f32_16x16x32_bf16 v[112:115], v[236:239], v[172:175], v[112:115]
	v_mfma_f32_16x16x32_bf16 v[100:103], v[228:231], v[180:183], v[100:103]
	v_mfma_f32_16x16x32_bf16 v[96:99], v[236:239], v[180:183], v[96:99]
	v_mfma_f32_16x16x32_bf16 v[84:87], v[228:231], v[188:191], v[84:87]
	v_mfma_f32_16x16x32_bf16 v[80:83], v[236:239], v[188:191], v[80:83]
	v_mfma_f32_16x16x32_bf16 v[68:71], v[228:231], v[220:223], v[68:71]
	v_mfma_f32_16x16x32_bf16 v[64:67], v[236:239], v[220:223], v[64:67]
	s_waitcnt lgkmcnt(0)
	v_mfma_f32_16x16x32_bf16 v[116:119], v[232:235], v[176:179], v[116:119]
	v_mfma_f32_16x16x32_bf16 v[112:115], v[240:243], v[176:179], v[112:115]
	v_mfma_f32_16x16x32_bf16 v[100:103], v[232:235], v[184:187], v[100:103]
	v_mfma_f32_16x16x32_bf16 v[96:99], v[240:243], v[184:187], v[96:99]
	v_mfma_f32_16x16x32_bf16 v[84:87], v[232:235], v[216:219], v[84:87]
	v_mfma_f32_16x16x32_bf16 v[80:83], v[240:243], v[216:219], v[80:83]
	v_mfma_f32_16x16x32_bf16 v[68:71], v[232:235], v[224:227], v[68:71]
	v_mfma_f32_16x16x32_bf16 v[64:67], v[240:243], v[224:227], v[64:67]
	s_mov_b32 m0, s17
	v_lshl_add_u64 v[246:247], s[24:25], 0, v[132:133]
	s_barrier
	ds_read_b128 v[172:175], v155 offset:16384
	ds_read_b128 v[180:183], v155 offset:18432
	ds_read_b128 v[188:191], v155 offset:20480
	ds_read_b128 v[220:223], v155 offset:22528
	ds_read_b128 v[176:179], v155 offset:17408
	ds_read_b128 v[184:187], v155 offset:19456
	ds_read_b128 v[216:219], v155 offset:21504
	ds_read_b128 v[224:227], v155 offset:23552
	global_load_lds_dwordx4 v132, s[24:25]
	v_lshl_add_u64 v[248:249], s[24:25], 0, v[128:129]
	s_mov_b32 m0, s31
	s_nop 0
	global_load_lds_dwordx4 v128, s[24:25]
	s_waitcnt vmcnt(10)
	s_barrier
	s_waitcnt lgkmcnt(4)
	v_mfma_f32_16x16x32_bf16 v[60:63], v[156:159], v[172:175], v[60:63]
	v_mfma_f32_16x16x32_bf16 v[56:59], v[164:167], v[172:175], v[56:59]
	v_mfma_f32_16x16x32_bf16 v[44:47], v[156:159], v[180:183], v[44:47]
	v_mfma_f32_16x16x32_bf16 v[40:43], v[164:167], v[180:183], v[40:43]
	v_mfma_f32_16x16x32_bf16 v[28:31], v[156:159], v[188:191], v[28:31]
	v_mfma_f32_16x16x32_bf16 v[24:27], v[164:167], v[188:191], v[24:27]
	v_mfma_f32_16x16x32_bf16 v[12:15], v[156:159], v[220:223], v[12:15]
	v_mfma_f32_16x16x32_bf16 v[8:11], v[164:167], v[220:223], v[8:11]
	s_waitcnt lgkmcnt(0)
	v_mfma_f32_16x16x32_bf16 v[60:63], v[160:163], v[176:179], v[60:63]
	v_mfma_f32_16x16x32_bf16 v[56:59], v[168:171], v[176:179], v[56:59]
	v_mfma_f32_16x16x32_bf16 v[44:47], v[160:163], v[184:187], v[44:47]
	v_mfma_f32_16x16x32_bf16 v[40:43], v[168:171], v[184:187], v[40:43]
	v_mfma_f32_16x16x32_bf16 v[28:31], v[160:163], v[216:219], v[28:31]
	v_mfma_f32_16x16x32_bf16 v[24:27], v[168:171], v[216:219], v[24:27]
	v_mfma_f32_16x16x32_bf16 v[12:15], v[160:163], v[224:227], v[12:15]
	v_mfma_f32_16x16x32_bf16 v[8:11], v[168:171], v[224:227], v[8:11]
	s_barrier
	s_add_u32 s48, s22, 0x40000
	s_addc_u32 s49, s23, 0
	s_add_i32 s47, s50, s29
	s_mov_b32 m0, s47
	s_nop 0
	global_load_lds_dwordx4 v132, s[48:49]
	s_add_i32 m0, s47, 0x2000
	s_nop 0
	global_load_lds_dwordx4 v128, s[48:49]
	v_add_u32_e32 v168, 0x18000, v154
	ds_read_b128 v[156:159], v168
	ds_read_b128 v[160:163], v168 offset:1024
	ds_read_b128 v[164:167], v168 offset:2048
	ds_read_b128 v[168:171], v168 offset:3072
	s_waitcnt vmcnt(10)
	s_barrier
	v_mfma_f32_16x16x32_bf16 v[52:55], v[228:231], v[172:175], v[52:55]
	v_mfma_f32_16x16x32_bf16 v[48:51], v[236:239], v[172:175], v[48:51]
	v_mfma_f32_16x16x32_bf16 v[36:39], v[228:231], v[180:183], v[36:39]
	v_mfma_f32_16x16x32_bf16 v[32:35], v[236:239], v[180:183], v[32:35]
	v_mfma_f32_16x16x32_bf16 v[20:23], v[228:231], v[188:191], v[20:23]
	v_mfma_f32_16x16x32_bf16 v[16:19], v[236:239], v[188:191], v[16:19]
	v_mfma_f32_16x16x32_bf16 v[4:7], v[228:231], v[220:223], v[4:7]
	v_mfma_f32_16x16x32_bf16 v[0:3], v[236:239], v[220:223], v[0:3]
	v_mfma_f32_16x16x32_bf16 v[52:55], v[232:235], v[176:179], v[52:55]
	v_mfma_f32_16x16x32_bf16 v[48:51], v[240:243], v[176:179], v[48:51]
	v_mfma_f32_16x16x32_bf16 v[36:39], v[232:235], v[184:187], v[36:39]
	v_mfma_f32_16x16x32_bf16 v[32:35], v[240:243], v[184:187], v[32:35]
	v_mfma_f32_16x16x32_bf16 v[20:23], v[232:235], v[216:219], v[20:23]
	v_mfma_f32_16x16x32_bf16 v[16:19], v[240:243], v[216:219], v[16:19]
	v_mfma_f32_16x16x32_bf16 v[4:7], v[232:235], v[224:227], v[4:7]
	v_mfma_f32_16x16x32_bf16 v[0:3], v[240:243], v[224:227], v[0:3]
	s_add_i32 s47, 0, 0x18000
	s_barrier
	s_add_u32 s24, s24, 0x40000
	s_addc_u32 s25, s25, 0
	s_mov_b32 m0, s34
	ds_read_b128 v[172:175], v155 offset:32768
	ds_read_b128 v[180:183], v155 offset:34816
	ds_read_b128 v[188:191], v155 offset:36864
	ds_read_b128 v[220:223], v155 offset:38912
	ds_read_b128 v[176:179], v155 offset:33792
	ds_read_b128 v[184:187], v155 offset:35840
	ds_read_b128 v[216:219], v155 offset:37888
	ds_read_b128 v[224:227], v155 offset:39936
	global_load_lds_dwordx4 v132, s[24:25]
	s_mov_b32 m0, s35
	s_nop 0
	global_load_lds_dwordx4 v128, s[24:25]
	s_waitcnt lgkmcnt(8)
	s_waitcnt vmcnt(10)
	s_barrier
	s_waitcnt lgkmcnt(4)
	v_mfma_f32_16x16x32_bf16 v[124:127], v[156:159], v[172:175], v[124:127]
	v_mfma_f32_16x16x32_bf16 v[120:123], v[164:167], v[172:175], v[120:123]
	v_mfma_f32_16x16x32_bf16 v[108:111], v[156:159], v[180:183], v[108:111]
	v_mfma_f32_16x16x32_bf16 v[104:107], v[164:167], v[180:183], v[104:107]
	v_mfma_f32_16x16x32_bf16 v[92:95], v[156:159], v[188:191], v[92:95]
	v_mfma_f32_16x16x32_bf16 v[88:91], v[164:167], v[188:191], v[88:91]
	v_mfma_f32_16x16x32_bf16 v[76:79], v[156:159], v[220:223], v[76:79]
	v_mfma_f32_16x16x32_bf16 v[72:75], v[164:167], v[220:223], v[72:75]
	s_waitcnt lgkmcnt(0)
	v_mfma_f32_16x16x32_bf16 v[124:127], v[160:163], v[176:179], v[124:127]
	v_mfma_f32_16x16x32_bf16 v[120:123], v[168:171], v[176:179], v[120:123]
	v_mfma_f32_16x16x32_bf16 v[108:111], v[160:163], v[184:187], v[108:111]
	v_mfma_f32_16x16x32_bf16 v[104:107], v[168:171], v[184:187], v[104:107]
	v_mfma_f32_16x16x32_bf16 v[92:95], v[160:163], v[216:219], v[92:95]
	v_mfma_f32_16x16x32_bf16 v[88:91], v[168:171], v[216:219], v[88:91]
	v_mfma_f32_16x16x32_bf16 v[76:79], v[160:163], v[224:227], v[76:79]
	v_mfma_f32_16x16x32_bf16 v[72:75], v[168:171], v[224:227], v[72:75]
	s_barrier
	s_add_i32 s24, 0, 0x1c000
	s_add_i32 s25, s47, s29
	v_add_u32_e32 v200, s24, v154
	s_mov_b32 m0, s25
	ds_read_b128 v[228:231], v200
	ds_read_b128 v[236:239], v200 offset:2048
	ds_read_b128 v[232:235], v200 offset:1024
	ds_read_b128 v[240:243], v200 offset:3072
	s_add_u32 s98, s22, 0x80
	s_addc_u32 s99, s23, 0
	global_load_lds_dwordx4 v132, s[98:99]
	s_add_i32 m0, s25, 0x2000
	s_nop 0
	global_load_lds_dwordx4 v128, s[98:99]
	s_waitcnt vmcnt(10)
	s_barrier
	s_waitcnt lgkmcnt(2)
	v_mfma_f32_16x16x32_bf16 v[116:119], v[228:231], v[172:175], v[116:119]
	v_mfma_f32_16x16x32_bf16 v[112:115], v[236:239], v[172:175], v[112:115]
	v_mfma_f32_16x16x32_bf16 v[100:103], v[228:231], v[180:183], v[100:103]
	v_mfma_f32_16x16x32_bf16 v[96:99], v[236:239], v[180:183], v[96:99]
	v_mfma_f32_16x16x32_bf16 v[84:87], v[228:231], v[188:191], v[84:87]
	v_mfma_f32_16x16x32_bf16 v[80:83], v[236:239], v[188:191], v[80:83]
	v_mfma_f32_16x16x32_bf16 v[68:71], v[228:231], v[220:223], v[68:71]
	v_mfma_f32_16x16x32_bf16 v[64:67], v[236:239], v[220:223], v[64:67]
	s_waitcnt lgkmcnt(0)
	v_mfma_f32_16x16x32_bf16 v[116:119], v[232:235], v[176:179], v[116:119]
	v_mfma_f32_16x16x32_bf16 v[112:115], v[240:243], v[176:179], v[112:115]
	v_mfma_f32_16x16x32_bf16 v[100:103], v[232:235], v[184:187], v[100:103]
	v_mfma_f32_16x16x32_bf16 v[96:99], v[240:243], v[184:187], v[96:99]
	v_mfma_f32_16x16x32_bf16 v[84:87], v[232:235], v[216:219], v[84:87]
	v_mfma_f32_16x16x32_bf16 v[80:83], v[240:243], v[216:219], v[80:83]
	v_mfma_f32_16x16x32_bf16 v[68:71], v[232:235], v[224:227], v[68:71]
	v_mfma_f32_16x16x32_bf16 v[64:67], v[240:243], v[224:227], v[64:67]
	s_mov_b32 m0, s36
	v_lshl_add_u64 v[152:153], v[246:247], 0, s[66:67]
	s_barrier
	ds_read_b128 v[172:175], v155 offset:49152
	ds_read_b128 v[180:183], v155 offset:51200
	ds_read_b128 v[188:191], v155 offset:53248
	ds_read_b128 v[220:223], v155 offset:55296
	ds_read_b128 v[176:179], v155 offset:50176
	ds_read_b128 v[184:187], v155 offset:52224
	ds_read_b128 v[216:219], v155 offset:54272
	ds_read_b128 v[224:227], v155 offset:56320
	global_load_lds_dwordx4 v[152:153], off
	v_lshl_add_u64 v[152:153], v[248:249], 0, s[66:67]
	s_mov_b32 m0, s37
	s_nop 0
	global_load_lds_dwordx4 v[152:153], off
	s_waitcnt vmcnt(10)
	s_barrier
	s_waitcnt lgkmcnt(4)
	v_mfma_f32_16x16x32_bf16 v[60:63], v[156:159], v[172:175], v[60:63]
	v_mfma_f32_16x16x32_bf16 v[56:59], v[164:167], v[172:175], v[56:59]
	v_mfma_f32_16x16x32_bf16 v[44:47], v[156:159], v[180:183], v[44:47]
	v_mfma_f32_16x16x32_bf16 v[40:43], v[164:167], v[180:183], v[40:43]
	v_mfma_f32_16x16x32_bf16 v[28:31], v[156:159], v[188:191], v[28:31]
	v_mfma_f32_16x16x32_bf16 v[24:27], v[164:167], v[188:191], v[24:27]
	v_mfma_f32_16x16x32_bf16 v[12:15], v[156:159], v[220:223], v[12:15]
	v_mfma_f32_16x16x32_bf16 v[8:11], v[164:167], v[220:223], v[8:11]
	s_waitcnt lgkmcnt(0)
	v_mfma_f32_16x16x32_bf16 v[60:63], v[160:163], v[176:179], v[60:63]
	v_mfma_f32_16x16x32_bf16 v[56:59], v[168:171], v[176:179], v[56:59]
	v_mfma_f32_16x16x32_bf16 v[44:47], v[160:163], v[184:187], v[44:47]
	v_mfma_f32_16x16x32_bf16 v[40:43], v[168:171], v[184:187], v[40:43]
	v_mfma_f32_16x16x32_bf16 v[28:31], v[160:163], v[216:219], v[28:31]
	v_mfma_f32_16x16x32_bf16 v[24:27], v[168:171], v[216:219], v[24:27]
	v_mfma_f32_16x16x32_bf16 v[12:15], v[160:163], v[224:227], v[12:15]
	v_mfma_f32_16x16x32_bf16 v[8:11], v[168:171], v[224:227], v[8:11]
	s_barrier
	s_add_u32 s22, s22, 0x40080
	s_addc_u32 s23, s23, 0
	s_add_i32 s24, s24, s29
	s_mov_b32 m0, s24
	s_nop 0
	global_load_lds_dwordx4 v132, s[22:23]
	s_add_i32 m0, s24, 0x2000
	s_nop 0
	global_load_lds_dwordx4 v128, s[22:23]
	v_add_u32_e32 v168, 0x10000, v154
	ds_read_b128 v[156:159], v168
	ds_read_b128 v[160:163], v168 offset:1024
	ds_read_b128 v[164:167], v168 offset:2048
	ds_read_b128 v[168:171], v168 offset:3072
	s_waitcnt vmcnt(10)
	s_barrier
	v_mfma_f32_16x16x32_bf16 v[52:55], v[228:231], v[172:175], v[52:55]
	v_mfma_f32_16x16x32_bf16 v[48:51], v[236:239], v[172:175], v[48:51]
	v_mfma_f32_16x16x32_bf16 v[36:39], v[228:231], v[180:183], v[36:39]
	v_mfma_f32_16x16x32_bf16 v[32:35], v[236:239], v[180:183], v[32:35]
	v_mfma_f32_16x16x32_bf16 v[20:23], v[228:231], v[188:191], v[20:23]
	v_mfma_f32_16x16x32_bf16 v[16:19], v[236:239], v[188:191], v[16:19]
	v_mfma_f32_16x16x32_bf16 v[4:7], v[228:231], v[220:223], v[4:7]
	v_mfma_f32_16x16x32_bf16 v[0:3], v[236:239], v[220:223], v[0:3]
	v_mfma_f32_16x16x32_bf16 v[52:55], v[232:235], v[176:179], v[52:55]
	v_mfma_f32_16x16x32_bf16 v[48:51], v[240:243], v[176:179], v[48:51]
	v_mfma_f32_16x16x32_bf16 v[36:39], v[232:235], v[184:187], v[36:39]
	v_mfma_f32_16x16x32_bf16 v[32:35], v[240:243], v[184:187], v[32:35]
	v_mfma_f32_16x16x32_bf16 v[20:23], v[232:235], v[216:219], v[20:23]
	v_mfma_f32_16x16x32_bf16 v[16:19], v[240:243], v[216:219], v[16:19]
	v_mfma_f32_16x16x32_bf16 v[4:7], v[232:235], v[224:227], v[4:7]
	v_mfma_f32_16x16x32_bf16 v[0:3], v[240:243], v[224:227], v[0:3]
	s_add_i32 s46, s46, 2
	s_add_u32 s18, s18, 0x100
	s_addc_u32 s19, s19, 0
	s_add_u32 s44, s44, 0x100
	s_addc_u32 s45, s45, 0
	s_cmp_gt_u32 s46, 13
	s_barrier
	s_cbranch_scc0 .LBB0_1104
	s_waitcnt lgkmcnt(0)
	v_mov_b32_e32 v153, v135
	s_mov_b64 s[18:19], s[0:1]
	s_load_dwordx2 s[18:19], s[18:19], 0x88
	s_nop 0
	v_readfirstlane_b32 s7, v153
	s_ashr_i32 s9, s7, 2
	s_lshr_b32 s7, s7, 1
	s_lshl_b32 s22, s41, 7
	s_and_b32 s7, s7, 0x60
	s_andn2_b32 s9, s9, 63
	s_or_b32 s7, s7, s22
	v_lshrrev_b32_e32 v152, 1, v153
	v_and_or_b32 v152, v152, 24, s7
	v_and_or_b32 v153, v153, 15, s9
	v_lshl_add_u32 v156, s16, 8, v153
	v_ashrrev_i32_e32 v153, 31, v152
	v_mov_b32_e32 v168, 0xbfb8aa3b
	v_mov_b32_e32 v169, 0xbfb8aa3b
	v_mov_b32_e32 v170, 1.0
	v_mov_b32_e32 v171, 1.0
	v_pk_mul_f32 v[160:161], v[124:125], v[168:169]
	v_pk_mul_f32 v[162:163], v[126:127], v[168:169]
	v_pk_mul_f32 v[164:165], v[116:117], v[168:169]
	v_pk_mul_f32 v[166:167], v[118:119], v[168:169]
	v_exp_f32_e32 v160, v160
	v_exp_f32_e32 v161, v161
	v_exp_f32_e32 v162, v162
	v_exp_f32_e32 v163, v163
	v_exp_f32_e32 v164, v164
	v_exp_f32_e32 v165, v165
	v_exp_f32_e32 v166, v166
	v_exp_f32_e32 v167, v167
	s_waitcnt lgkmcnt(0)
	v_lshl_add_u64 v[152:153], v[152:153], 1, s[18:19]
	s_mov_b64 s[18:19], 0xa2a4400
	v_lshl_add_u64 v[152:153], v[152:153], 0, s[18:19]
	s_and_b64 vcc, exec, s[4:5]
	s_mov_b32 s41, s6
	s_mov_b32 s16, s8
	s_mov_b64 s[22:23], s[12:13]
	v_pk_add_f32 v[160:161], v[160:161], v[170:171]
	v_pk_add_f32 v[162:163], v[162:163], v[170:171]
	v_pk_add_f32 v[164:165], v[164:165], v[170:171]
	v_pk_add_f32 v[166:167], v[166:167], v[170:171]
	v_rcp_f32_e32 v160, v160
	v_rcp_f32_e32 v161, v161
	v_rcp_f32_e32 v162, v162
	v_rcp_f32_e32 v163, v163
	v_rcp_f32_e32 v164, v164
	v_rcp_f32_e32 v165, v165
	v_rcp_f32_e32 v166, v166
	v_rcp_f32_e32 v167, v167
	v_mov_b32_e32 v158, v156
	v_mad_i64_i32 v[158:159], s[18:19], v158, s73, v[152:153]
	v_pk_mul_f32 v[124:125], v[124:125], v[160:161]
	v_pk_mul_f32 v[126:127], v[126:127], v[162:163]
	v_pk_mul_f32 v[116:117], v[116:117], v[164:165]
	v_pk_mul_f32 v[118:119], v[118:119], v[166:167]
	v_pk_mul_f32 v[120:121], v[120:121], v[124:125]
	v_pk_mul_f32 v[122:123], v[122:123], v[126:127]
	v_pk_mul_f32 v[112:113], v[112:113], v[116:117]
	v_pk_mul_f32 v[114:115], v[114:115], v[118:119]
	v_cvt_pk_bf16_f32 v120, v120, v121
	v_cvt_pk_bf16_f32 v121, v122, v123
	v_cvt_pk_bf16_f32 v122, v112, v113
	v_cvt_pk_bf16_f32 v123, v114, v115
	global_store_dwordx4 v[158:159], v[120:123], off sc1
	v_pk_mul_f32 v[160:161], v[108:109], v[168:169]
	v_pk_mul_f32 v[162:163], v[110:111], v[168:169]
	v_pk_mul_f32 v[164:165], v[100:101], v[168:169]
	v_pk_mul_f32 v[166:167], v[102:103], v[168:169]
	v_exp_f32_e32 v160, v160
	v_exp_f32_e32 v161, v161
	v_exp_f32_e32 v162, v162
	v_exp_f32_e32 v163, v163
	v_exp_f32_e32 v164, v164
	v_exp_f32_e32 v165, v165
	v_exp_f32_e32 v166, v166
	v_exp_f32_e32 v167, v167
	v_pk_add_f32 v[160:161], v[160:161], v[170:171]
	v_pk_add_f32 v[162:163], v[162:163], v[170:171]
	v_pk_add_f32 v[164:165], v[164:165], v[170:171]
	v_pk_add_f32 v[166:167], v[166:167], v[170:171]
	v_rcp_f32_e32 v160, v160
	v_rcp_f32_e32 v161, v161
	v_rcp_f32_e32 v162, v162
	v_rcp_f32_e32 v163, v163
	v_rcp_f32_e32 v164, v164
	v_rcp_f32_e32 v165, v165
	v_rcp_f32_e32 v166, v166
	v_rcp_f32_e32 v167, v167
	v_add_u32_e32 v158, 0x10, v156
	v_mad_i64_i32 v[158:159], s[18:19], v158, s73, v[152:153]
	v_pk_mul_f32 v[108:109], v[108:109], v[160:161]
	v_pk_mul_f32 v[110:111], v[110:111], v[162:163]
	v_pk_mul_f32 v[100:101], v[100:101], v[164:165]
	v_pk_mul_f32 v[102:103], v[102:103], v[166:167]
	v_pk_mul_f32 v[104:105], v[104:105], v[108:109]
	v_pk_mul_f32 v[106:107], v[106:107], v[110:111]
	v_pk_mul_f32 v[96:97], v[96:97], v[100:101]
	v_pk_mul_f32 v[98:99], v[98:99], v[102:103]
	v_cvt_pk_bf16_f32 v104, v104, v105
	v_cvt_pk_bf16_f32 v105, v106, v107
	v_cvt_pk_bf16_f32 v106, v96, v97
	v_cvt_pk_bf16_f32 v107, v98, v99
	global_store_dwordx4 v[158:159], v[104:107], off sc1
	v_pk_mul_f32 v[160:161], v[92:93], v[168:169]
	v_pk_mul_f32 v[162:163], v[94:95], v[168:169]
	v_pk_mul_f32 v[164:165], v[84:85], v[168:169]
	v_pk_mul_f32 v[166:167], v[86:87], v[168:169]
	v_exp_f32_e32 v160, v160
	v_exp_f32_e32 v161, v161
	v_exp_f32_e32 v162, v162
	v_exp_f32_e32 v163, v163
	v_exp_f32_e32 v164, v164
	v_exp_f32_e32 v165, v165
	v_exp_f32_e32 v166, v166
	v_exp_f32_e32 v167, v167
	v_pk_add_f32 v[160:161], v[160:161], v[170:171]
	v_pk_add_f32 v[162:163], v[162:163], v[170:171]
	v_pk_add_f32 v[164:165], v[164:165], v[170:171]
	v_pk_add_f32 v[166:167], v[166:167], v[170:171]
	v_rcp_f32_e32 v160, v160
	v_rcp_f32_e32 v161, v161
	v_rcp_f32_e32 v162, v162
	v_rcp_f32_e32 v163, v163
	v_rcp_f32_e32 v164, v164
	v_rcp_f32_e32 v165, v165
	v_rcp_f32_e32 v166, v166
	v_rcp_f32_e32 v167, v167
	v_add_u32_e32 v158, 0x20, v156
	v_mad_i64_i32 v[158:159], s[18:19], v158, s73, v[152:153]
	v_pk_mul_f32 v[92:93], v[92:93], v[160:161]
	v_pk_mul_f32 v[94:95], v[94:95], v[162:163]
	v_pk_mul_f32 v[84:85], v[84:85], v[164:165]
	v_pk_mul_f32 v[86:87], v[86:87], v[166:167]
	v_pk_mul_f32 v[88:89], v[88:89], v[92:93]
	v_pk_mul_f32 v[90:91], v[90:91], v[94:95]
	v_pk_mul_f32 v[80:81], v[80:81], v[84:85]
	v_pk_mul_f32 v[82:83], v[82:83], v[86:87]
	v_cvt_pk_bf16_f32 v88, v88, v89
	v_cvt_pk_bf16_f32 v89, v90, v91
	v_cvt_pk_bf16_f32 v90, v80, v81
	v_cvt_pk_bf16_f32 v91, v82, v83
	global_store_dwordx4 v[158:159], v[88:91], off sc1
	v_pk_mul_f32 v[160:161], v[76:77], v[168:169]
	v_pk_mul_f32 v[162:163], v[78:79], v[168:169]
	v_pk_mul_f32 v[164:165], v[68:69], v[168:169]
	v_pk_mul_f32 v[166:167], v[70:71], v[168:169]
	v_exp_f32_e32 v160, v160
	v_exp_f32_e32 v161, v161
	v_exp_f32_e32 v162, v162
	v_exp_f32_e32 v163, v163
	v_exp_f32_e32 v164, v164
	v_exp_f32_e32 v165, v165
	v_exp_f32_e32 v166, v166
	v_exp_f32_e32 v167, v167
	v_pk_add_f32 v[160:161], v[160:161], v[170:171]
	v_pk_add_f32 v[162:163], v[162:163], v[170:171]
	v_pk_add_f32 v[164:165], v[164:165], v[170:171]
	v_pk_add_f32 v[166:167], v[166:167], v[170:171]
	v_rcp_f32_e32 v160, v160
	v_rcp_f32_e32 v161, v161
	v_rcp_f32_e32 v162, v162
	v_rcp_f32_e32 v163, v163
	v_rcp_f32_e32 v164, v164
	v_rcp_f32_e32 v165, v165
	v_rcp_f32_e32 v166, v166
	v_rcp_f32_e32 v167, v167
	v_add_u32_e32 v158, 0x30, v156
	v_mad_i64_i32 v[158:159], s[18:19], v158, s73, v[152:153]
	v_pk_mul_f32 v[76:77], v[76:77], v[160:161]
	v_pk_mul_f32 v[78:79], v[78:79], v[162:163]
	v_pk_mul_f32 v[68:69], v[68:69], v[164:165]
	v_pk_mul_f32 v[70:71], v[70:71], v[166:167]
	v_pk_mul_f32 v[72:73], v[72:73], v[76:77]
	v_pk_mul_f32 v[74:75], v[74:75], v[78:79]
	v_pk_mul_f32 v[64:65], v[64:65], v[68:69]
	v_pk_mul_f32 v[66:67], v[66:67], v[70:71]
	v_cvt_pk_bf16_f32 v72, v72, v73
	v_cvt_pk_bf16_f32 v73, v74, v75
	v_cvt_pk_bf16_f32 v74, v64, v65
	v_cvt_pk_bf16_f32 v75, v66, v67
	global_store_dwordx4 v[158:159], v[72:75], off sc1
	v_pk_mul_f32 v[160:161], v[60:61], v[168:169]
	v_pk_mul_f32 v[162:163], v[62:63], v[168:169]
	v_pk_mul_f32 v[164:165], v[52:53], v[168:169]
	v_pk_mul_f32 v[166:167], v[54:55], v[168:169]
	v_exp_f32_e32 v160, v160
	v_exp_f32_e32 v161, v161
	v_exp_f32_e32 v162, v162
	v_exp_f32_e32 v163, v163
	v_exp_f32_e32 v164, v164
	v_exp_f32_e32 v165, v165
	v_exp_f32_e32 v166, v166
	v_exp_f32_e32 v167, v167
	v_pk_add_f32 v[160:161], v[160:161], v[170:171]
	v_pk_add_f32 v[162:163], v[162:163], v[170:171]
	v_pk_add_f32 v[164:165], v[164:165], v[170:171]
	v_pk_add_f32 v[166:167], v[166:167], v[170:171]
	v_rcp_f32_e32 v160, v160
	v_rcp_f32_e32 v161, v161
	v_rcp_f32_e32 v162, v162
	v_rcp_f32_e32 v163, v163
	v_rcp_f32_e32 v164, v164
	v_rcp_f32_e32 v165, v165
	v_rcp_f32_e32 v166, v166
	v_rcp_f32_e32 v167, v167
	v_add_u32_e32 v158, 0x80, v156
	v_mad_i64_i32 v[158:159], s[18:19], v158, s73, v[152:153]
	v_pk_mul_f32 v[60:61], v[60:61], v[160:161]
	v_pk_mul_f32 v[62:63], v[62:63], v[162:163]
	v_pk_mul_f32 v[52:53], v[52:53], v[164:165]
	v_pk_mul_f32 v[54:55], v[54:55], v[166:167]
	v_pk_mul_f32 v[56:57], v[56:57], v[60:61]
	v_pk_mul_f32 v[58:59], v[58:59], v[62:63]
	v_pk_mul_f32 v[48:49], v[48:49], v[52:53]
	v_pk_mul_f32 v[50:51], v[50:51], v[54:55]
	v_cvt_pk_bf16_f32 v56, v56, v57
	v_cvt_pk_bf16_f32 v57, v58, v59
	v_cvt_pk_bf16_f32 v58, v48, v49
	v_cvt_pk_bf16_f32 v59, v50, v51
	global_store_dwordx4 v[158:159], v[56:59], off sc1
	v_pk_mul_f32 v[160:161], v[44:45], v[168:169]
	v_pk_mul_f32 v[162:163], v[46:47], v[168:169]
	v_pk_mul_f32 v[164:165], v[36:37], v[168:169]
	v_pk_mul_f32 v[166:167], v[38:39], v[168:169]
	v_exp_f32_e32 v160, v160
	v_exp_f32_e32 v161, v161
	v_exp_f32_e32 v162, v162
	v_exp_f32_e32 v163, v163
	v_exp_f32_e32 v164, v164
	v_exp_f32_e32 v165, v165
	v_exp_f32_e32 v166, v166
	v_exp_f32_e32 v167, v167
	v_pk_add_f32 v[160:161], v[160:161], v[170:171]
	v_pk_add_f32 v[162:163], v[162:163], v[170:171]
	v_pk_add_f32 v[164:165], v[164:165], v[170:171]
	v_pk_add_f32 v[166:167], v[166:167], v[170:171]
	v_rcp_f32_e32 v160, v160
	v_rcp_f32_e32 v161, v161
	v_rcp_f32_e32 v162, v162
	v_rcp_f32_e32 v163, v163
	v_rcp_f32_e32 v164, v164
	v_rcp_f32_e32 v165, v165
	v_rcp_f32_e32 v166, v166
	v_rcp_f32_e32 v167, v167
	v_add_u32_e32 v158, 0x90, v156
	v_mad_i64_i32 v[158:159], s[18:19], v158, s73, v[152:153]
	v_pk_mul_f32 v[44:45], v[44:45], v[160:161]
	v_pk_mul_f32 v[46:47], v[46:47], v[162:163]
	v_pk_mul_f32 v[36:37], v[36:37], v[164:165]
	v_pk_mul_f32 v[38:39], v[38:39], v[166:167]
	v_pk_mul_f32 v[40:41], v[40:41], v[44:45]
	v_pk_mul_f32 v[42:43], v[42:43], v[46:47]
	v_pk_mul_f32 v[32:33], v[32:33], v[36:37]
	v_pk_mul_f32 v[34:35], v[34:35], v[38:39]
	v_cvt_pk_bf16_f32 v40, v40, v41
	v_cvt_pk_bf16_f32 v41, v42, v43
	v_cvt_pk_bf16_f32 v42, v32, v33
	v_cvt_pk_bf16_f32 v43, v34, v35
	global_store_dwordx4 v[158:159], v[40:43], off sc1
	v_pk_mul_f32 v[160:161], v[28:29], v[168:169]
	v_pk_mul_f32 v[162:163], v[30:31], v[168:169]
	v_pk_mul_f32 v[164:165], v[20:21], v[168:169]
	v_pk_mul_f32 v[166:167], v[22:23], v[168:169]
	v_exp_f32_e32 v160, v160
	v_exp_f32_e32 v161, v161
	v_exp_f32_e32 v162, v162
	v_exp_f32_e32 v163, v163
	v_exp_f32_e32 v164, v164
	v_exp_f32_e32 v165, v165
	v_exp_f32_e32 v166, v166
	v_exp_f32_e32 v167, v167
	v_pk_add_f32 v[160:161], v[160:161], v[170:171]
	v_pk_add_f32 v[162:163], v[162:163], v[170:171]
	v_pk_add_f32 v[164:165], v[164:165], v[170:171]
	v_pk_add_f32 v[166:167], v[166:167], v[170:171]
	v_rcp_f32_e32 v160, v160
	v_rcp_f32_e32 v161, v161
	v_rcp_f32_e32 v162, v162
	v_rcp_f32_e32 v163, v163
	v_rcp_f32_e32 v164, v164
	v_rcp_f32_e32 v165, v165
	v_rcp_f32_e32 v166, v166
	v_rcp_f32_e32 v167, v167
	v_add_u32_e32 v158, 0xa0, v156
	v_mad_i64_i32 v[158:159], s[18:19], v158, s73, v[152:153]
	v_pk_mul_f32 v[28:29], v[28:29], v[160:161]
	v_pk_mul_f32 v[30:31], v[30:31], v[162:163]
	v_pk_mul_f32 v[20:21], v[20:21], v[164:165]
	v_pk_mul_f32 v[22:23], v[22:23], v[166:167]
	v_pk_mul_f32 v[24:25], v[24:25], v[28:29]
	v_pk_mul_f32 v[26:27], v[26:27], v[30:31]
	v_pk_mul_f32 v[16:17], v[16:17], v[20:21]
	v_pk_mul_f32 v[18:19], v[18:19], v[22:23]
	v_cvt_pk_bf16_f32 v24, v24, v25
	v_cvt_pk_bf16_f32 v25, v26, v27
	v_cvt_pk_bf16_f32 v26, v16, v17
	v_cvt_pk_bf16_f32 v27, v18, v19
	global_store_dwordx4 v[158:159], v[24:27], off sc1
	v_pk_mul_f32 v[160:161], v[12:13], v[168:169]
	v_pk_mul_f32 v[162:163], v[14:15], v[168:169]
	v_pk_mul_f32 v[164:165], v[4:5], v[168:169]
	v_pk_mul_f32 v[166:167], v[6:7], v[168:169]
	v_exp_f32_e32 v160, v160
	v_exp_f32_e32 v161, v161
	v_exp_f32_e32 v162, v162
	v_exp_f32_e32 v163, v163
	v_exp_f32_e32 v164, v164
	v_exp_f32_e32 v165, v165
	v_exp_f32_e32 v166, v166
	v_exp_f32_e32 v167, v167
	v_pk_add_f32 v[160:161], v[160:161], v[170:171]
	v_pk_add_f32 v[162:163], v[162:163], v[170:171]
	v_pk_add_f32 v[164:165], v[164:165], v[170:171]
	v_pk_add_f32 v[166:167], v[166:167], v[170:171]
	v_rcp_f32_e32 v160, v160
	v_rcp_f32_e32 v161, v161
	v_rcp_f32_e32 v162, v162
	v_rcp_f32_e32 v163, v163
	v_rcp_f32_e32 v164, v164
	v_rcp_f32_e32 v165, v165
	v_rcp_f32_e32 v166, v166
	v_rcp_f32_e32 v167, v167
	v_add_u32_e32 v158, 0xb0, v156
	v_mad_i64_i32 v[158:159], s[18:19], v158, s73, v[152:153]
	v_pk_mul_f32 v[12:13], v[12:13], v[160:161]
	v_pk_mul_f32 v[14:15], v[14:15], v[162:163]
	v_pk_mul_f32 v[4:5], v[4:5], v[164:165]
	v_pk_mul_f32 v[6:7], v[6:7], v[166:167]
	v_pk_mul_f32 v[8:9], v[8:9], v[12:13]
	v_pk_mul_f32 v[10:11], v[10:11], v[14:15]
	v_pk_mul_f32 v[0:1], v[0:1], v[4:5]
	v_pk_mul_f32 v[2:3], v[2:3], v[6:7]
	v_cvt_pk_bf16_f32 v8, v8, v9
	v_cvt_pk_bf16_f32 v9, v10, v11
	v_cvt_pk_bf16_f32 v10, v0, v1
	v_cvt_pk_bf16_f32 v11, v2, v3
	global_store_dwordx4 v[158:159], v[8:11], off sc1
	s_mov_b64 s[18:19], s[10:11]
	s_cbranch_vccz .LBB0_1101
	s_waitcnt vmcnt(0)
	s_cmpk_gt_u32 s14, 0xff
	s_cbranch_scc1 .LBB0_1108
	s_barrier

.LBB0_1234:
	s_add_i32 s40, s10, 2
	s_add_u32 s12, s8, 0x80
	s_addc_u32 s11, s9, 0
	s_add_i32 s41, 0, 0x10000
	s_cmp_eq_u32 s29, s10
	s_cselect_b32 s10, s2, s12
	s_cselect_b32 s11, s3, s11
	s_cselect_b32 s13, s7, s39
	s_cselect_b32 s12, s6, s38
	s_add_i32 m0, s22, 0xc000
	ds_read_b128 v[172:175], v155
	ds_read_b128 v[180:183], v155 offset:2048
	ds_read_b128 v[188:191], v155 offset:4096
	ds_read_b128 v[220:223], v155 offset:6144
	ds_read_b128 v[176:179], v155 offset:1024
	ds_read_b128 v[184:187], v155 offset:3072
	ds_read_b128 v[216:219], v155 offset:5120
	ds_read_b128 v[224:227], v155 offset:7168
	global_load_lds_dwordx4 v130, s[8:9]
	s_add_i32 m0, s22, 0xe000
	s_nop 0
	global_load_lds_dwordx4 v150, s[8:9]
	s_waitcnt lgkmcnt(8)
	s_waitcnt vmcnt(10)
	s_barrier
	s_waitcnt lgkmcnt(4)
	v_mfma_f32_16x16x32_bf16 v[124:127], v[156:159], v[172:175], v[124:127]
	v_mfma_f32_16x16x32_bf16 v[120:123], v[164:167], v[172:175], v[120:123]
	v_mfma_f32_16x16x32_bf16 v[116:119], v[156:159], v[180:183], v[116:119]
	v_mfma_f32_16x16x32_bf16 v[108:111], v[164:167], v[180:183], v[108:111]
	v_mfma_f32_16x16x32_bf16 v[100:103], v[156:159], v[188:191], v[100:103]
	v_mfma_f32_16x16x32_bf16 v[92:95], v[164:167], v[188:191], v[92:95]
	v_mfma_f32_16x16x32_bf16 v[84:87], v[156:159], v[220:223], v[84:87]
	v_mfma_f32_16x16x32_bf16 v[76:79], v[164:167], v[220:223], v[76:79]
	s_waitcnt lgkmcnt(0)
	v_mfma_f32_16x16x32_bf16 v[124:127], v[160:163], v[176:179], v[124:127]
	v_mfma_f32_16x16x32_bf16 v[120:123], v[168:171], v[176:179], v[120:123]
	v_mfma_f32_16x16x32_bf16 v[116:119], v[160:163], v[184:187], v[116:119]
	v_mfma_f32_16x16x32_bf16 v[108:111], v[168:171], v[184:187], v[108:111]
	v_mfma_f32_16x16x32_bf16 v[100:103], v[160:163], v[216:219], v[100:103]
	v_mfma_f32_16x16x32_bf16 v[92:95], v[168:171], v[216:219], v[92:95]
	v_mfma_f32_16x16x32_bf16 v[84:87], v[160:163], v[224:227], v[84:87]
	v_mfma_f32_16x16x32_bf16 v[76:79], v[168:171], v[224:227], v[76:79]
	s_barrier
	s_add_i32 s42, 0, 0x14000
	v_add_u32_e32 v152, s42, v154
	s_add_i32 s41, s41, s19
	ds_read_b128 v[228:231], v152
	ds_read_b128 v[236:239], v152 offset:2048
	ds_read_b128 v[232:235], v152 offset:1024
	ds_read_b128 v[240:243], v152 offset:3072
	v_lshl_add_u64 v[152:153], s[12:13], 0, v[132:133]
	s_mov_b32 m0, s41
	v_lshl_add_u64 v[244:245], s[12:13], 0, v[128:129]
	global_load_lds_dwordx4 v132, s[12:13]
	s_add_i32 m0, s41, 0x2000
	s_nop 0
	global_load_lds_dwordx4 v128, s[12:13]
	s_waitcnt vmcnt(10)
	s_barrier
	s_waitcnt lgkmcnt(2)
	v_mfma_f32_16x16x32_bf16 v[112:115], v[228:231], v[172:175], v[112:115]
	v_mfma_f32_16x16x32_bf16 v[104:107], v[236:239], v[172:175], v[104:107]
	v_mfma_f32_16x16x32_bf16 v[96:99], v[228:231], v[180:183], v[96:99]
	v_mfma_f32_16x16x32_bf16 v[88:91], v[236:239], v[180:183], v[88:91]
	v_mfma_f32_16x16x32_bf16 v[80:83], v[228:231], v[188:191], v[80:83]
	v_mfma_f32_16x16x32_bf16 v[72:75], v[236:239], v[188:191], v[72:75]
	v_mfma_f32_16x16x32_bf16 v[68:71], v[228:231], v[220:223], v[68:71]
	v_mfma_f32_16x16x32_bf16 v[64:67], v[236:239], v[220:223], v[64:67]
	s_waitcnt lgkmcnt(0)
	v_mfma_f32_16x16x32_bf16 v[112:115], v[232:235], v[176:179], v[112:115]
	v_mfma_f32_16x16x32_bf16 v[104:107], v[240:243], v[176:179], v[104:107]
	v_mfma_f32_16x16x32_bf16 v[96:99], v[232:235], v[184:187], v[96:99]
	v_mfma_f32_16x16x32_bf16 v[88:91], v[240:243], v[184:187], v[88:91]
	v_mfma_f32_16x16x32_bf16 v[80:83], v[232:235], v[216:219], v[80:83]
	v_mfma_f32_16x16x32_bf16 v[72:75], v[240:243], v[216:219], v[72:75]
	v_mfma_f32_16x16x32_bf16 v[68:71], v[232:235], v[224:227], v[68:71]
	v_mfma_f32_16x16x32_bf16 v[64:67], v[240:243], v[224:227], v[64:67]
	s_mov_b32 m0, s22
	v_lshl_add_u64 v[246:247], s[10:11], 0, v[132:133]
	s_barrier
	ds_read_b128 v[172:175], v155 offset:16384
	ds_read_b128 v[180:183], v155 offset:18432
	ds_read_b128 v[188:191], v155 offset:20480
	ds_read_b128 v[220:223], v155 offset:22528
	ds_read_b128 v[176:179], v155 offset:17408
	ds_read_b128 v[184:187], v155 offset:19456
	ds_read_b128 v[216:219], v155 offset:21504
	ds_read_b128 v[224:227], v155 offset:23552
	global_load_lds_dwordx4 v132, s[10:11]
	v_lshl_add_u64 v[248:249], s[10:11], 0, v[128:129]
	s_mov_b32 m0, s23
	s_nop 0
	global_load_lds_dwordx4 v128, s[10:11]
	s_waitcnt vmcnt(10)
	s_barrier
	s_waitcnt lgkmcnt(4)
	v_mfma_f32_16x16x32_bf16 v[60:63], v[156:159], v[172:175], v[60:63]
	v_mfma_f32_16x16x32_bf16 v[56:59], v[164:167], v[172:175], v[56:59]
	v_mfma_f32_16x16x32_bf16 v[52:55], v[156:159], v[180:183], v[52:55]
	v_mfma_f32_16x16x32_bf16 v[44:47], v[164:167], v[180:183], v[44:47]
	v_mfma_f32_16x16x32_bf16 v[36:39], v[156:159], v[188:191], v[36:39]
	v_mfma_f32_16x16x32_bf16 v[28:31], v[164:167], v[188:191], v[28:31]
	v_mfma_f32_16x16x32_bf16 v[20:23], v[156:159], v[220:223], v[20:23]
	v_mfma_f32_16x16x32_bf16 v[12:15], v[164:167], v[220:223], v[12:15]
	s_waitcnt lgkmcnt(0)
	v_mfma_f32_16x16x32_bf16 v[60:63], v[160:163], v[176:179], v[60:63]
	v_mfma_f32_16x16x32_bf16 v[56:59], v[168:171], v[176:179], v[56:59]
	v_mfma_f32_16x16x32_bf16 v[52:55], v[160:163], v[184:187], v[52:55]
	v_mfma_f32_16x16x32_bf16 v[44:47], v[168:171], v[184:187], v[44:47]
	v_mfma_f32_16x16x32_bf16 v[36:39], v[160:163], v[216:219], v[36:39]
	v_mfma_f32_16x16x32_bf16 v[28:31], v[168:171], v[216:219], v[28:31]
	v_mfma_f32_16x16x32_bf16 v[20:23], v[160:163], v[224:227], v[20:23]
	v_mfma_f32_16x16x32_bf16 v[12:15], v[168:171], v[224:227], v[12:15]
	s_barrier
	s_add_u32 s12, s12, s58
	s_addc_u32 s13, s13, 0
	s_add_i32 s41, s42, s19
	v_lshl_add_u64 v[250:251], s[12:13], 0, v[132:133]
	s_mov_b32 m0, s41
	v_lshl_add_u64 v[252:253], s[12:13], 0, v[128:129]
	global_load_lds_dwordx4 v132, s[12:13]
	s_add_i32 m0, s41, 0x2000
	s_nop 0
	global_load_lds_dwordx4 v128, s[12:13]
	v_add_u32_e32 v168, 0x18000, v154
	ds_read_b128 v[156:159], v168
	ds_read_b128 v[160:163], v168 offset:1024
	ds_read_b128 v[164:167], v168 offset:2048
	ds_read_b128 v[168:171], v168 offset:3072
	s_waitcnt vmcnt(10)
	s_barrier
	v_mfma_f32_16x16x32_bf16 v[48:51], v[228:231], v[172:175], v[48:51]
	v_mfma_f32_16x16x32_bf16 v[40:43], v[236:239], v[172:175], v[40:43]
	v_mfma_f32_16x16x32_bf16 v[32:35], v[228:231], v[180:183], v[32:35]
	v_mfma_f32_16x16x32_bf16 v[24:27], v[236:239], v[180:183], v[24:27]
	v_mfma_f32_16x16x32_bf16 v[16:19], v[228:231], v[188:191], v[16:19]
	v_mfma_f32_16x16x32_bf16 v[8:11], v[236:239], v[188:191], v[8:11]
	v_mfma_f32_16x16x32_bf16 v[4:7], v[228:231], v[220:223], v[4:7]
	v_mfma_f32_16x16x32_bf16 v[0:3], v[236:239], v[220:223], v[0:3]
	v_mfma_f32_16x16x32_bf16 v[48:51], v[232:235], v[176:179], v[48:51]
	v_mfma_f32_16x16x32_bf16 v[40:43], v[240:243], v[176:179], v[40:43]
	v_mfma_f32_16x16x32_bf16 v[32:35], v[232:235], v[184:187], v[32:35]
	v_mfma_f32_16x16x32_bf16 v[24:27], v[240:243], v[184:187], v[24:27]
	v_mfma_f32_16x16x32_bf16 v[16:19], v[232:235], v[216:219], v[16:19]
	v_mfma_f32_16x16x32_bf16 v[8:11], v[240:243], v[216:219], v[8:11]
	v_mfma_f32_16x16x32_bf16 v[4:7], v[232:235], v[224:227], v[4:7]
	v_mfma_f32_16x16x32_bf16 v[0:3], v[240:243], v[224:227], v[0:3]
	s_add_i32 s12, 0, 0x18000
	s_barrier
	s_add_u32 s10, s10, s58
	s_addc_u32 s11, s11, 0
	s_mov_b32 m0, s24
	ds_read_b128 v[172:175], v155 offset:32768
	ds_read_b128 v[180:183], v155 offset:34816
	ds_read_b128 v[188:191], v155 offset:36864
	ds_read_b128 v[220:223], v155 offset:38912
	ds_read_b128 v[176:179], v155 offset:33792
	ds_read_b128 v[184:187], v155 offset:35840
	ds_read_b128 v[216:219], v155 offset:37888
	ds_read_b128 v[224:227], v155 offset:39936
	global_load_lds_dwordx4 v132, s[10:11]
	s_mov_b32 m0, s25
	s_nop 0
	global_load_lds_dwordx4 v128, s[10:11]
	s_waitcnt lgkmcnt(8)
	s_waitcnt vmcnt(10)
	s_barrier
	s_waitcnt lgkmcnt(4)
	v_mfma_f32_16x16x32_bf16 v[124:127], v[156:159], v[172:175], v[124:127]
	v_mfma_f32_16x16x32_bf16 v[120:123], v[164:167], v[172:175], v[120:123]
	v_mfma_f32_16x16x32_bf16 v[116:119], v[156:159], v[180:183], v[116:119]
	v_mfma_f32_16x16x32_bf16 v[108:111], v[164:167], v[180:183], v[108:111]
	v_mfma_f32_16x16x32_bf16 v[100:103], v[156:159], v[188:191], v[100:103]
	v_mfma_f32_16x16x32_bf16 v[92:95], v[164:167], v[188:191], v[92:95]
	v_mfma_f32_16x16x32_bf16 v[84:87], v[156:159], v[220:223], v[84:87]
	v_mfma_f32_16x16x32_bf16 v[76:79], v[164:167], v[220:223], v[76:79]
	s_waitcnt lgkmcnt(0)
	v_mfma_f32_16x16x32_bf16 v[124:127], v[160:163], v[176:179], v[124:127]
	v_mfma_f32_16x16x32_bf16 v[120:123], v[168:171], v[176:179], v[120:123]
	v_mfma_f32_16x16x32_bf16 v[116:119], v[160:163], v[184:187], v[116:119]
	v_mfma_f32_16x16x32_bf16 v[108:111], v[168:171], v[184:187], v[108:111]
	v_mfma_f32_16x16x32_bf16 v[100:103], v[160:163], v[216:219], v[100:103]
	v_mfma_f32_16x16x32_bf16 v[92:95], v[168:171], v[216:219], v[92:95]
	v_mfma_f32_16x16x32_bf16 v[84:87], v[160:163], v[224:227], v[84:87]
	v_mfma_f32_16x16x32_bf16 v[76:79], v[168:171], v[224:227], v[76:79]
	s_barrier
	s_add_i32 s10, 0, 0x1c000
	s_add_i32 s11, s12, s19
	v_add_u32_e32 v200, s10, v154
	v_lshl_add_u64 v[152:153], v[152:153], 0, s[66:67]
	s_mov_b32 m0, s11
	ds_read_b128 v[228:231], v200
	ds_read_b128 v[236:239], v200 offset:2048
	ds_read_b128 v[232:235], v200 offset:1024
	ds_read_b128 v[240:243], v200 offset:3072
	global_load_lds_dwordx4 v[152:153], off
	v_lshl_add_u64 v[152:153], v[244:245], 0, s[66:67]
	s_add_i32 m0, s11, 0x2000
	s_nop 0
	global_load_lds_dwordx4 v[152:153], off
	s_waitcnt vmcnt(10)
	s_barrier
	s_waitcnt lgkmcnt(2)
	v_mfma_f32_16x16x32_bf16 v[112:115], v[228:231], v[172:175], v[112:115]
	v_mfma_f32_16x16x32_bf16 v[104:107], v[236:239], v[172:175], v[104:107]
	v_mfma_f32_16x16x32_bf16 v[96:99], v[228:231], v[180:183], v[96:99]
	v_mfma_f32_16x16x32_bf16 v[88:91], v[236:239], v[180:183], v[88:91]
	v_mfma_f32_16x16x32_bf16 v[80:83], v[228:231], v[188:191], v[80:83]
	v_mfma_f32_16x16x32_bf16 v[72:75], v[236:239], v[188:191], v[72:75]
	v_mfma_f32_16x16x32_bf16 v[68:71], v[228:231], v[220:223], v[68:71]
	v_mfma_f32_16x16x32_bf16 v[64:67], v[236:239], v[220:223], v[64:67]
	s_waitcnt lgkmcnt(0)
	v_mfma_f32_16x16x32_bf16 v[112:115], v[232:235], v[176:179], v[112:115]
	v_mfma_f32_16x16x32_bf16 v[104:107], v[240:243], v[176:179], v[104:107]
	v_mfma_f32_16x16x32_bf16 v[96:99], v[232:235], v[184:187], v[96:99]
	v_mfma_f32_16x16x32_bf16 v[88:91], v[240:243], v[184:187], v[88:91]
	v_mfma_f32_16x16x32_bf16 v[80:83], v[232:235], v[216:219], v[80:83]
	v_mfma_f32_16x16x32_bf16 v[72:75], v[240:243], v[216:219], v[72:75]
	v_mfma_f32_16x16x32_bf16 v[68:71], v[232:235], v[224:227], v[68:71]
	v_mfma_f32_16x16x32_bf16 v[64:67], v[240:243], v[224:227], v[64:67]
	s_mov_b32 m0, s26
	v_lshl_add_u64 v[152:153], v[246:247], 0, s[66:67]
	s_barrier
	ds_read_b128 v[172:175], v155 offset:49152
	ds_read_b128 v[180:183], v155 offset:51200
	ds_read_b128 v[188:191], v155 offset:53248
	ds_read_b128 v[220:223], v155 offset:55296
	ds_read_b128 v[176:179], v155 offset:50176
	ds_read_b128 v[184:187], v155 offset:52224
	ds_read_b128 v[216:219], v155 offset:54272
	ds_read_b128 v[224:227], v155 offset:56320
	global_load_lds_dwordx4 v[152:153], off
	v_lshl_add_u64 v[152:153], v[248:249], 0, s[66:67]
	s_mov_b32 m0, s27
	s_nop 0
	global_load_lds_dwordx4 v[152:153], off
	s_waitcnt vmcnt(10)
	s_barrier
	s_waitcnt lgkmcnt(4)
	v_mfma_f32_16x16x32_bf16 v[60:63], v[156:159], v[172:175], v[60:63]
	v_mfma_f32_16x16x32_bf16 v[56:59], v[164:167], v[172:175], v[56:59]
	v_mfma_f32_16x16x32_bf16 v[52:55], v[156:159], v[180:183], v[52:55]
	v_mfma_f32_16x16x32_bf16 v[44:47], v[164:167], v[180:183], v[44:47]
	v_mfma_f32_16x16x32_bf16 v[36:39], v[156:159], v[188:191], v[36:39]
	v_mfma_f32_16x16x32_bf16 v[28:31], v[164:167], v[188:191], v[28:31]
	v_mfma_f32_16x16x32_bf16 v[20:23], v[156:159], v[220:223], v[20:23]
	v_mfma_f32_16x16x32_bf16 v[12:15], v[164:167], v[220:223], v[12:15]
	s_waitcnt lgkmcnt(0)
	v_mfma_f32_16x16x32_bf16 v[60:63], v[160:163], v[176:179], v[60:63]
	v_mfma_f32_16x16x32_bf16 v[56:59], v[168:171], v[176:179], v[56:59]
	v_mfma_f32_16x16x32_bf16 v[52:55], v[160:163], v[184:187], v[52:55]
	v_mfma_f32_16x16x32_bf16 v[44:47], v[168:171], v[184:187], v[44:47]
	v_mfma_f32_16x16x32_bf16 v[36:39], v[160:163], v[216:219], v[36:39]
	v_mfma_f32_16x16x32_bf16 v[28:31], v[168:171], v[216:219], v[28:31]
	v_mfma_f32_16x16x32_bf16 v[20:23], v[160:163], v[224:227], v[20:23]
	v_mfma_f32_16x16x32_bf16 v[12:15], v[168:171], v[224:227], v[12:15]
	s_barrier
	s_add_i32 s10, s10, s19
	v_lshl_add_u64 v[152:153], v[250:251], 0, s[66:67]
	s_mov_b32 m0, s10
	s_nop 0
	global_load_lds_dwordx4 v[152:153], off
	v_lshl_add_u64 v[152:153], v[252:253], 0, s[66:67]
	s_add_i32 m0, s10, 0x2000
	s_nop 0
	global_load_lds_dwordx4 v[152:153], off
	v_add_u32_e32 v168, 0x10000, v154
	ds_read_b128 v[156:159], v168
	ds_read_b128 v[160:163], v168 offset:1024
	ds_read_b128 v[164:167], v168 offset:2048
	ds_read_b128 v[168:171], v168 offset:3072
	s_waitcnt vmcnt(10)
	s_barrier
	v_mfma_f32_16x16x32_bf16 v[48:51], v[228:231], v[172:175], v[48:51]
	v_mfma_f32_16x16x32_bf16 v[40:43], v[236:239], v[172:175], v[40:43]
	v_mfma_f32_16x16x32_bf16 v[32:35], v[228:231], v[180:183], v[32:35]
	v_mfma_f32_16x16x32_bf16 v[24:27], v[236:239], v[180:183], v[24:27]
	v_mfma_f32_16x16x32_bf16 v[16:19], v[228:231], v[188:191], v[16:19]
	v_mfma_f32_16x16x32_bf16 v[8:11], v[236:239], v[188:191], v[8:11]
	v_mfma_f32_16x16x32_bf16 v[4:7], v[228:231], v[220:223], v[4:7]
	v_mfma_f32_16x16x32_bf16 v[0:3], v[236:239], v[220:223], v[0:3]
	v_mfma_f32_16x16x32_bf16 v[48:51], v[232:235], v[176:179], v[48:51]
	v_mfma_f32_16x16x32_bf16 v[40:43], v[240:243], v[176:179], v[40:43]
	v_mfma_f32_16x16x32_bf16 v[32:35], v[232:235], v[184:187], v[32:35]
	v_mfma_f32_16x16x32_bf16 v[24:27], v[240:243], v[184:187], v[24:27]
	v_mfma_f32_16x16x32_bf16 v[16:19], v[232:235], v[216:219], v[16:19]
	v_mfma_f32_16x16x32_bf16 v[8:11], v[240:243], v[216:219], v[8:11]
	v_mfma_f32_16x16x32_bf16 v[4:7], v[232:235], v[224:227], v[4:7]
	v_mfma_f32_16x16x32_bf16 v[0:3], v[240:243], v[224:227], v[0:3]
	s_add_u32 s8, s8, 0x100
	s_addc_u32 s9, s9, 0
	s_add_u32 s38, s38, 0x100
	s_addc_u32 s39, s39, 0
	s_cmp_ge_u32 s40, s28
	s_mov_b32 s10, s40
	s_barrier
	s_cbranch_scc0 .LBB0_1234
	s_waitcnt lgkmcnt(0)
	v_mov_b32_e32 v152, v135
	s_mov_b64 s[8:9], s[0:1]
	v_readfirstlane_b32 s10, v152
	s_ashr_i32 s12, s10, 2
	s_load_dwordx2 s[8:9], s[8:9], 0x88
	s_lshl_b32 s11, s36, 8
	s_andn2_b32 s12, s12, 63
	s_lshr_b32 s10, s10, 1
	s_add_i32 s12, s12, s11
	s_lshl_b32 s11, s37, 8
	s_and_b32 s10, s10, 0x60
	v_and_or_b32 v156, v152, 15, s12
	s_or_b32 s10, s10, s11
	v_lshrrev_b32_e32 v152, 1, v152
	v_and_or_b32 v152, v152, 24, s10
	v_ashrrev_i32_e32 v153, 31, v152
	s_waitcnt lgkmcnt(0)
	v_lshl_add_u64 v[152:153], v[152:153], 1, s[8:9]
	s_mov_b64 s[8:9], 0x62a4400
	v_ashrrev_i32_e32 v157, 31, v156
	v_lshl_add_u64 v[158:159], v[152:153], 0, s[8:9]
	v_lshlrev_b64 v[152:153], 11, v[156:157]
	v_lshl_add_u64 v[152:153], v[158:159], 0, v[152:153]
	s_mov_b64 s[8:9], 0x40000
	v_cvt_pk_bf16_f32 v68, v68, v69
	v_cvt_pk_bf16_f32 v69, v70, v71
	v_cvt_pk_bf16_f32 v70, v64, v65
	v_lshl_add_u64 v[64:65], v[152:153], 0, s[8:9]
	s_mov_b32 s8, 0x40000
	v_cvt_pk_bf16_f32 v60, v60, v61
	v_cvt_pk_bf16_f32 v61, v62, v63
	v_cvt_pk_bf16_f32 v62, v56, v57
	v_add_co_u32_e32 v56, vcc, s8, v152
	v_cvt_pk_bf16_f32 v48, v48, v49
	v_cvt_pk_bf16_f32 v49, v50, v51
	s_mov_b64 s[8:9], 0x48000
	s_nop 0
	v_addc_co_u32_e32 v57, vcc, 0, v153, vcc
	v_cvt_pk_bf16_f32 v50, v40, v41
	v_cvt_pk_bf16_f32 v51, v42, v43
	global_store_dwordx4 v[64:65], v[48:51], off offset:256 sc1
	v_cvt_pk_bf16_f32 v42, v44, v45
	v_cvt_pk_bf16_f32 v32, v32, v33
	v_cvt_pk_bf16_f32 v33, v34, v35
	v_cvt_pk_bf16_f32 v112, v112, v113
	v_cvt_pk_bf16_f32 v113, v114, v115
	s_nop 1
	v_lshl_add_u64 v[48:49], v[152:153], 0, s[8:9]
	s_mov_b32 s8, 0x48000
	v_add_co_u32_e32 v44, vcc, s8, v152
	s_mov_b64 s[8:9], 0x50000
	v_cvt_pk_bf16_f32 v114, v104, v105
	v_or_b32_e32 v104, 16, v156
	v_addc_co_u32_e32 v45, vcc, 0, v153, vcc
	v_cvt_pk_bf16_f32 v34, v24, v25
	v_cvt_pk_bf16_f32 v35, v26, v27
	global_store_dwordx4 v[48:49], v[32:35], off offset:256 sc1
	v_ashrrev_i32_e32 v105, 31, v104
	v_cvt_pk_bf16_f32 v96, v96, v97
	v_cvt_pk_bf16_f32 v97, v98, v99
	v_cvt_pk_bf16_f32 v98, v88, v89
	v_or_b32_e32 v88, 32, v156
	v_lshl_add_u64 v[32:33], v[152:153], 0, s[8:9]
	s_mov_b32 s8, 0x50000
	v_cvt_pk_bf16_f32 v26, v28, v29
	v_add_co_u32_e32 v28, vcc, s8, v152
	v_cvt_pk_bf16_f32 v16, v16, v17
	v_cvt_pk_bf16_f32 v17, v18, v19
	s_mov_b64 s[8:9], 0x58000
	v_lshlrev_b64 v[104:105], 11, v[104:105]
	v_ashrrev_i32_e32 v89, 31, v88
	v_cvt_pk_bf16_f32 v80, v80, v81
	v_cvt_pk_bf16_f32 v81, v82, v83
	v_cvt_pk_bf16_f32 v82, v72, v73
	v_or_b32_e32 v72, 48, v156
	v_addc_co_u32_e32 v29, vcc, 0, v153, vcc
	v_cvt_pk_bf16_f32 v18, v8, v9
	v_cvt_pk_bf16_f32 v19, v10, v11
	global_store_dwordx4 v[32:33], v[16:19], off offset:256 sc1
	v_cvt_pk_bf16_f32 v115, v106, v107
	global_store_dwordx4 v[152:153], v[112:115], off offset:256 sc1
	v_lshlrev_b64 v[88:89], 11, v[88:89]
	v_lshl_add_u64 v[16:17], v[152:153], 0, s[8:9]
	s_mov_b32 s8, 0x58000
	v_lshl_add_u64 v[112:113], v[158:159], 0, v[104:105]
	v_ashrrev_i32_e32 v73, 31, v72
	v_cvt_pk_bf16_f32 v10, v12, v13
	v_add_co_u32_e32 v12, vcc, s8, v152
	v_cvt_pk_bf16_f32 v99, v90, v91
	global_store_dwordx4 v[112:113], v[96:99], off offset:256 sc1
	v_lshlrev_b64 v[72:73], 11, v[72:73]
	v_addc_co_u32_e32 v13, vcc, 0, v153, vcc
	v_lshl_add_u64 v[96:97], v[158:159], 0, v[88:89]
	v_cvt_pk_bf16_f32 v83, v74, v75
	global_store_dwordx4 v[96:97], v[80:83], off offset:256 sc1
	s_and_b64 vcc, exec, s[4:5]
	s_mov_b32 s37, s34
	v_lshl_add_u64 v[80:81], v[158:159], 0, v[72:73]
	s_mov_b32 s36, s35
	s_mov_b64 s[10:11], s[6:7]
	s_mov_b64 s[12:13], s[2:3]
	v_cvt_pk_bf16_f32 v124, v124, v125
	v_cvt_pk_bf16_f32 v125, v126, v127
	v_cvt_pk_bf16_f32 v126, v120, v121
	v_cvt_pk_bf16_f32 v127, v122, v123
	global_store_dwordx4 v[152:153], v[124:127], off sc1
	v_cvt_pk_bf16_f32 v104, v116, v117
	v_cvt_pk_bf16_f32 v105, v118, v119
	v_cvt_pk_bf16_f32 v106, v108, v109
	v_cvt_pk_bf16_f32 v107, v110, v111
	global_store_dwordx4 v[112:113], v[104:107], off sc1
	v_cvt_pk_bf16_f32 v88, v100, v101
	v_cvt_pk_bf16_f32 v89, v102, v103
	v_cvt_pk_bf16_f32 v90, v92, v93
	v_cvt_pk_bf16_f32 v91, v94, v95
	global_store_dwordx4 v[96:97], v[88:91], off sc1
	v_cvt_pk_bf16_f32 v72, v84, v85
	v_cvt_pk_bf16_f32 v73, v86, v87
	v_cvt_pk_bf16_f32 v74, v76, v77
	v_cvt_pk_bf16_f32 v75, v78, v79
	global_store_dwordx4 v[80:81], v[72:75], off sc1
	v_cvt_pk_bf16_f32 v71, v66, v67
	global_store_dwordx4 v[80:81], v[68:71], off offset:256 sc1
	v_cvt_pk_bf16_f32 v63, v58, v59
	global_store_dwordx4 v[56:57], v[60:63], off sc1
	v_cvt_pk_bf16_f32 v40, v52, v53
	v_cvt_pk_bf16_f32 v41, v54, v55
	v_cvt_pk_bf16_f32 v43, v46, v47
	global_store_dwordx4 v[44:45], v[40:43], off sc1
	v_cvt_pk_bf16_f32 v24, v36, v37
	v_cvt_pk_bf16_f32 v25, v38, v39
	v_cvt_pk_bf16_f32 v27, v30, v31
	global_store_dwordx4 v[28:29], v[24:27], off sc1
	v_cvt_pk_bf16_f32 v8, v20, v21
	v_cvt_pk_bf16_f32 v9, v22, v23
	v_cvt_pk_bf16_f32 v11, v14, v15
	global_store_dwordx4 v[12:13], v[8:11], off sc1
	v_cvt_pk_bf16_f32 v4, v4, v5
	v_cvt_pk_bf16_f32 v5, v6, v7
	v_cvt_pk_bf16_f32 v6, v0, v1
	v_cvt_pk_bf16_f32 v7, v2, v3
	global_store_dwordx4 v[16:17], v[4:7], off offset:256 sc1
	s_cbranch_vccz .LBB0_1223
	s_waitcnt vmcnt(0)
	s_cmpk_gt_u32 s14, 0xff
	s_cbranch_scc1 .LBB0_1238
	s_barrier
